# weight conversion: 4 source tiles in flight (with nt loads)
# baseline (speedup 1.0000x reference)
.Lwc0_tj_3:
	s_load_dwordx2 s[2:3], s[0:1], s41
	s_add_u32 s52, s4, s36
	s_addc_u32 s53, s5, 0
	v_mad_u32_u24 v223, v225, s99, v226
	v_writelane_b32 v229, s52, 16
	v_writelane_b32 v229, s53, 17
	v_writelane_b32 v229, s32, 18
	v_writelane_b32 v229, s44, 19
	s_add_u32 s100, s100, s67
	s_waitcnt lgkmcnt(0)
	s_add_u32 s38, s2, s38
	s_addc_u32 s39, s3, 0
	global_load_dwordx4 v[170:173], v223, s[38:39] nt
	s_add_u32 s38, s38, s37
	s_addc_u32 s39, s39, 0
	global_load_dwordx4 v[174:177], v223, s[38:39] nt
	s_add_u32 s38, s38, s37
	s_addc_u32 s39, s39, 0
	global_load_dwordx4 v[178:181], v223, s[38:39] nt
	s_add_u32 s38, s38, s37
	s_addc_u32 s39, s39, 0
	global_load_dwordx4 v[182:185], v223, s[38:39] nt
	s_cmp_ge_u32 s100, s66
	s_cbranch_scc1 .Lwc0_p3
	s_cmpk_ge_u32 s100, 0x900
	s_cbranch_scc1 .Lwc0_t3_4
	s_cmpk_ge_u32 s100, 0x380
	s_cbranch_scc1 .Lwc0_t2_4
	s_cmpk_ge_u32 s100, 0x280
	s_cbranch_scc1 .Lwc0_t1_4
	s_movk_i32 s41, 0x78
	s_sub_u32 s99, s100, 0
	s_mul_i32 s44, s99, 0x66667
	s_lshr_b32 s44, s44, 24
	s_mul_i32 s36, s44, 40
	s_sub_u32 s99, s99, s36
	s_mul_i32 s38, s44, 0xa0000
	s_lshl_b32 s36, s99, 8
	s_add_u32 s38, s38, s36
	s_add_u32 s38, s38, 0x0
	s_lshl_b32 s36, s99, 6
	s_mov_b32 s32, 0x10000
	s_mul_i32 s36, s36, 0x800
	s_lshl_b32 s44, s44, 7
	s_add_u32 s36, s36, s44
	s_add_u32 s36, s36, 0x0
	s_mov_b32 s37, 0x28000
	s_movk_i32 s44, 0x800
	s_mov_b32 s99, 0x2800
	s_branch .Lwc0_tj_4

.Lwc0_tj_4:
	s_load_dwordx2 s[2:3], s[0:1], s41
	s_add_u32 s52, s4, s36
	s_addc_u32 s53, s5, 0
	v_mad_u32_u24 v223, v225, s99, v226
	v_writelane_b32 v229, s52, 20
	v_writelane_b32 v229, s53, 21
	v_writelane_b32 v229, s32, 22
	v_writelane_b32 v229, s44, 23
	s_add_u32 s100, s100, s67
	s_waitcnt lgkmcnt(0)
	s_add_u32 s38, s2, s38
	s_addc_u32 s39, s3, 0
	global_load_dwordx4 v[186:189], v223, s[38:39] nt
	s_add_u32 s38, s38, s37
	s_addc_u32 s39, s39, 0
	global_load_dwordx4 v[190:193], v223, s[38:39] nt
	s_add_u32 s38, s38, s37
	s_addc_u32 s39, s39, 0
	global_load_dwordx4 v[194:197], v223, s[38:39] nt
	s_add_u32 s38, s38, s37
	s_addc_u32 s39, s39, 0
	global_load_dwordx4 v[198:201], v223, s[38:39] nt
.Lwc0_loop:
	s_waitcnt vmcnt(12)
	v_readlane_b32 s52, v229, 8
	v_readlane_b32 s53, v229, 9
	v_readlane_b32 s32, v229, 10
	v_readlane_b32 s35, v229, 11
	ds_write_b32 v218, v138 offset:0
	ds_write_b32 v218, v139 offset:4
	ds_write_b32 v218, v140 offset:8
	ds_write_b32 v218, v141 offset:12
	ds_write_b32 v218, v142 offset:4160
	ds_write_b32 v218, v143 offset:4164
	ds_write_b32 v218, v144 offset:4168
	ds_write_b32 v218, v145 offset:4172
	ds_write_b32 v218, v146 offset:8320
	ds_write_b32 v218, v147 offset:8324
	ds_write_b32 v218, v148 offset:8328
	ds_write_b32 v218, v149 offset:8332
	ds_write_b32 v218, v150 offset:12480
	ds_write_b32 v218, v151 offset:12484
	ds_write_b32 v218, v152 offset:12488
	ds_write_b32 v218, v153 offset:12492
	v_mad_u32_u24 v224, v227, s35, v228
	s_waitcnt lgkmcnt(0)
	s_barrier
	ds_read2_b32 v[138:139], v219 offset1:65
	ds_read2_b32 v[140:141], v219 offset0:130 offset1:195
	ds_read2_b32 v[142:143], v220 offset0:4 offset1:69
	ds_read2_b32 v[144:145], v220 offset0:134 offset1:199
	ds_read2_b32 v[146:147], v221 offset1:65
	ds_read2_b32 v[148:149], v221 offset0:130 offset1:195
	ds_read2_b32 v[150:151], v222 offset0:4 offset1:69
	ds_read2_b32 v[152:153], v222 offset0:134 offset1:199
	s_add_u32 s96, s52, s32
	s_addc_u32 s97, s53, 0
	s_waitcnt lgkmcnt(0)
	s_barrier
	v_cvt_pk_bf16_f32 v138, v138, v139
	v_cvt_pk_bf16_f32 v139, v140, v141
	v_cvt_pk_bf16_f32 v140, v142, v143
	v_cvt_pk_bf16_f32 v141, v144, v145
	v_cvt_pk_bf16_f32 v146, v146, v147
	v_cvt_pk_bf16_f32 v147, v148, v149
	v_cvt_pk_bf16_f32 v148, v150, v151
	v_cvt_pk_bf16_f32 v149, v152, v153
	global_store_dwordx4 v224, v[138:141], s[52:53]
	global_store_dwordx4 v224, v[146:149], s[96:97]
	s_cmp_ge_u32 s100, s66
	s_cbranch_scc1 .Lwc0_tail0
	s_cmpk_ge_u32 s100, 0x900
	s_cbranch_scc1 .Lwc0_t3_5
	s_cmpk_ge_u32 s100, 0x380
	s_cbranch_scc1 .Lwc0_t2_5
	s_cmpk_ge_u32 s100, 0x280
	s_cbranch_scc1 .Lwc0_t1_5
	s_movk_i32 s41, 0x78
	s_sub_u32 s99, s100, 0
	s_mul_i32 s44, s99, 0x66667
	s_lshr_b32 s44, s44, 24
	s_mul_i32 s36, s44, 40
	s_sub_u32 s99, s99, s36
	s_mul_i32 s38, s44, 0xa0000
	s_lshl_b32 s36, s99, 8
	s_add_u32 s38, s38, s36
	s_add_u32 s38, s38, 0x0
	s_lshl_b32 s36, s99, 6
	s_mov_b32 s32, 0x10000
	s_mul_i32 s36, s36, 0x800
	s_lshl_b32 s44, s44, 7
	s_add_u32 s36, s36, s44
	s_add_u32 s36, s36, 0x0
	s_mov_b32 s37, 0x28000
	s_movk_i32 s44, 0x800
	s_mov_b32 s99, 0x2800
	s_branch .Lwc0_tj_5

.Lwc0_tj_5:
	s_load_dwordx2 s[2:3], s[0:1], s41
	s_add_u32 s52, s4, s36
	s_addc_u32 s53, s5, 0
	v_mad_u32_u24 v223, v225, s99, v226
	v_writelane_b32 v229, s52, 8
	v_writelane_b32 v229, s53, 9
	v_writelane_b32 v229, s32, 10
	v_writelane_b32 v229, s44, 11
	s_add_u32 s100, s100, s67
	s_waitcnt lgkmcnt(0)
	s_add_u32 s38, s2, s38
	s_addc_u32 s39, s3, 0
	global_load_dwordx4 v[138:141], v223, s[38:39] nt
	s_add_u32 s38, s38, s37
	s_addc_u32 s39, s39, 0
	global_load_dwordx4 v[142:145], v223, s[38:39] nt
	s_add_u32 s38, s38, s37
	s_addc_u32 s39, s39, 0
	global_load_dwordx4 v[146:149], v223, s[38:39] nt
	s_add_u32 s38, s38, s37
	s_addc_u32 s39, s39, 0
	global_load_dwordx4 v[150:153], v223, s[38:39] nt
	s_waitcnt vmcnt(12)
	v_readlane_b32 s52, v229, 12
	v_readlane_b32 s53, v229, 13
	v_readlane_b32 s32, v229, 14
	v_readlane_b32 s35, v229, 15
	ds_write_b32 v218, v154 offset:0
	ds_write_b32 v218, v155 offset:4
	ds_write_b32 v218, v156 offset:8
	ds_write_b32 v218, v157 offset:12
	ds_write_b32 v218, v158 offset:4160
	ds_write_b32 v218, v159 offset:4164
	ds_write_b32 v218, v160 offset:4168
	ds_write_b32 v218, v161 offset:4172
	ds_write_b32 v218, v162 offset:8320
	ds_write_b32 v218, v163 offset:8324
	ds_write_b32 v218, v164 offset:8328
	ds_write_b32 v218, v165 offset:8332
	ds_write_b32 v218, v166 offset:12480
	ds_write_b32 v218, v167 offset:12484
	ds_write_b32 v218, v168 offset:12488
	ds_write_b32 v218, v169 offset:12492
	v_mad_u32_u24 v224, v227, s35, v228
	s_waitcnt lgkmcnt(0)
	s_barrier
	ds_read2_b32 v[154:155], v219 offset1:65
	ds_read2_b32 v[156:157], v219 offset0:130 offset1:195
	ds_read2_b32 v[158:159], v220 offset0:4 offset1:69
	ds_read2_b32 v[160:161], v220 offset0:134 offset1:199
	ds_read2_b32 v[162:163], v221 offset1:65
	ds_read2_b32 v[164:165], v221 offset0:130 offset1:195
	ds_read2_b32 v[166:167], v222 offset0:4 offset1:69
	ds_read2_b32 v[168:169], v222 offset0:134 offset1:199
	s_add_u32 s96, s52, s32
	s_addc_u32 s97, s53, 0
	s_waitcnt lgkmcnt(0)
	s_barrier
	v_cvt_pk_bf16_f32 v154, v154, v155
	v_cvt_pk_bf16_f32 v155, v156, v157
	v_cvt_pk_bf16_f32 v156, v158, v159
	v_cvt_pk_bf16_f32 v157, v160, v161
	v_cvt_pk_bf16_f32 v162, v162, v163
	v_cvt_pk_bf16_f32 v163, v164, v165
	v_cvt_pk_bf16_f32 v164, v166, v167
	v_cvt_pk_bf16_f32 v165, v168, v169
	global_store_dwordx4 v224, v[154:157], s[52:53]
	global_store_dwordx4 v224, v[162:165], s[96:97]
	s_cmp_ge_u32 s100, s66
	s_cbranch_scc1 .Lwc0_tail1
	s_cmpk_ge_u32 s100, 0x900
	s_cbranch_scc1 .Lwc0_t3_6
	s_cmpk_ge_u32 s100, 0x380
	s_cbranch_scc1 .Lwc0_t2_6
	s_cmpk_ge_u32 s100, 0x280
	s_cbranch_scc1 .Lwc0_t1_6
	s_movk_i32 s41, 0x78
	s_sub_u32 s99, s100, 0
	s_mul_i32 s44, s99, 0x66667
	s_lshr_b32 s44, s44, 24
	s_mul_i32 s36, s44, 40
	s_sub_u32 s99, s99, s36
	s_mul_i32 s38, s44, 0xa0000
	s_lshl_b32 s36, s99, 8
	s_add_u32 s38, s38, s36
	s_add_u32 s38, s38, 0x0
	s_lshl_b32 s36, s99, 6
	s_mov_b32 s32, 0x10000
	s_mul_i32 s36, s36, 0x800
	s_lshl_b32 s44, s44, 7
	s_add_u32 s36, s36, s44
	s_add_u32 s36, s36, 0x0
	s_mov_b32 s37, 0x28000
	s_movk_i32 s44, 0x800
	s_mov_b32 s99, 0x2800
	s_branch .Lwc0_tj_6

.Lwc0_tj_6:
	s_load_dwordx2 s[2:3], s[0:1], s41
	s_add_u32 s52, s4, s36
	s_addc_u32 s53, s5, 0
	v_mad_u32_u24 v223, v225, s99, v226
	v_writelane_b32 v229, s52, 12
	v_writelane_b32 v229, s53, 13
	v_writelane_b32 v229, s32, 14
	v_writelane_b32 v229, s44, 15
	s_add_u32 s100, s100, s67
	s_waitcnt lgkmcnt(0)
	s_add_u32 s38, s2, s38
	s_addc_u32 s39, s3, 0
	global_load_dwordx4 v[154:157], v223, s[38:39] nt
	s_add_u32 s38, s38, s37
	s_addc_u32 s39, s39, 0
	global_load_dwordx4 v[158:161], v223, s[38:39] nt
	s_add_u32 s38, s38, s37
	s_addc_u32 s39, s39, 0
	global_load_dwordx4 v[162:165], v223, s[38:39] nt
	s_add_u32 s38, s38, s37
	s_addc_u32 s39, s39, 0
	global_load_dwordx4 v[166:169], v223, s[38:39] nt
	s_waitcnt vmcnt(12)
	v_readlane_b32 s52, v229, 16
	v_readlane_b32 s53, v229, 17
	v_readlane_b32 s32, v229, 18
	v_readlane_b32 s35, v229, 19
	ds_write_b32 v218, v170 offset:0
	ds_write_b32 v218, v171 offset:4
	ds_write_b32 v218, v172 offset:8
	ds_write_b32 v218, v173 offset:12
	ds_write_b32 v218, v174 offset:4160
	ds_write_b32 v218, v175 offset:4164
	ds_write_b32 v218, v176 offset:4168
	ds_write_b32 v218, v177 offset:4172
	ds_write_b32 v218, v178 offset:8320
	ds_write_b32 v218, v179 offset:8324
	ds_write_b32 v218, v180 offset:8328
	ds_write_b32 v218, v181 offset:8332
	ds_write_b32 v218, v182 offset:12480
	ds_write_b32 v218, v183 offset:12484
	ds_write_b32 v218, v184 offset:12488
	ds_write_b32 v218, v185 offset:12492
	v_mad_u32_u24 v224, v227, s35, v228
	s_waitcnt lgkmcnt(0)
	s_barrier
	ds_read2_b32 v[170:171], v219 offset1:65
	ds_read2_b32 v[172:173], v219 offset0:130 offset1:195
	ds_read2_b32 v[174:175], v220 offset0:4 offset1:69
	ds_read2_b32 v[176:177], v220 offset0:134 offset1:199
	ds_read2_b32 v[178:179], v221 offset1:65
	ds_read2_b32 v[180:181], v221 offset0:130 offset1:195
	ds_read2_b32 v[182:183], v222 offset0:4 offset1:69
	ds_read2_b32 v[184:185], v222 offset0:134 offset1:199
	s_add_u32 s96, s52, s32
	s_addc_u32 s97, s53, 0
	s_waitcnt lgkmcnt(0)
	s_barrier
	v_cvt_pk_bf16_f32 v170, v170, v171
	v_cvt_pk_bf16_f32 v171, v172, v173
	v_cvt_pk_bf16_f32 v172, v174, v175
	v_cvt_pk_bf16_f32 v173, v176, v177
	v_cvt_pk_bf16_f32 v178, v178, v179
	v_cvt_pk_bf16_f32 v179, v180, v181
	v_cvt_pk_bf16_f32 v180, v182, v183
	v_cvt_pk_bf16_f32 v181, v184, v185
	global_store_dwordx4 v224, v[170:173], s[52:53]
	global_store_dwordx4 v224, v[178:181], s[96:97]
	s_cmp_ge_u32 s100, s66
	s_cbranch_scc1 .Lwc0_tail2
	s_cmpk_ge_u32 s100, 0x900
	s_cbranch_scc1 .Lwc0_t3_7
	s_cmpk_ge_u32 s100, 0x380
	s_cbranch_scc1 .Lwc0_t2_7
	s_cmpk_ge_u32 s100, 0x280
	s_cbranch_scc1 .Lwc0_t1_7
	s_movk_i32 s41, 0x78
	s_sub_u32 s99, s100, 0
	s_mul_i32 s44, s99, 0x66667
	s_lshr_b32 s44, s44, 24
	s_mul_i32 s36, s44, 40
	s_sub_u32 s99, s99, s36
	s_mul_i32 s38, s44, 0xa0000
	s_lshl_b32 s36, s99, 8
	s_add_u32 s38, s38, s36
	s_add_u32 s38, s38, 0x0
	s_lshl_b32 s36, s99, 6
	s_mov_b32 s32, 0x10000
	s_mul_i32 s36, s36, 0x800
	s_lshl_b32 s44, s44, 7
	s_add_u32 s36, s36, s44
	s_add_u32 s36, s36, 0x0
	s_mov_b32 s37, 0x28000
	s_movk_i32 s44, 0x800
	s_mov_b32 s99, 0x2800
	s_branch .Lwc0_tj_7

.Lwc0_tj_7:
	s_load_dwordx2 s[2:3], s[0:1], s41
	s_add_u32 s52, s4, s36
	s_addc_u32 s53, s5, 0
	v_mad_u32_u24 v223, v225, s99, v226
	v_writelane_b32 v229, s52, 16
	v_writelane_b32 v229, s53, 17
	v_writelane_b32 v229, s32, 18
	v_writelane_b32 v229, s44, 19
	s_add_u32 s100, s100, s67
	s_waitcnt lgkmcnt(0)
	s_add_u32 s38, s2, s38
	s_addc_u32 s39, s3, 0
	global_load_dwordx4 v[170:173], v223, s[38:39] nt
	s_add_u32 s38, s38, s37
	s_addc_u32 s39, s39, 0
	global_load_dwordx4 v[174:177], v223, s[38:39] nt
	s_add_u32 s38, s38, s37
	s_addc_u32 s39, s39, 0
	global_load_dwordx4 v[178:181], v223, s[38:39] nt
	s_add_u32 s38, s38, s37
	s_addc_u32 s39, s39, 0
	global_load_dwordx4 v[182:185], v223, s[38:39] nt
	s_waitcnt vmcnt(12)
	v_readlane_b32 s52, v229, 20
	v_readlane_b32 s53, v229, 21
	v_readlane_b32 s32, v229, 22
	v_readlane_b32 s35, v229, 23
	ds_write_b32 v218, v186 offset:0
	ds_write_b32 v218, v187 offset:4
	ds_write_b32 v218, v188 offset:8
	ds_write_b32 v218, v189 offset:12
	ds_write_b32 v218, v190 offset:4160
	ds_write_b32 v218, v191 offset:4164
	ds_write_b32 v218, v192 offset:4168
	ds_write_b32 v218, v193 offset:4172
	ds_write_b32 v218, v194 offset:8320
	ds_write_b32 v218, v195 offset:8324
	ds_write_b32 v218, v196 offset:8328
	ds_write_b32 v218, v197 offset:8332
	ds_write_b32 v218, v198 offset:12480
	ds_write_b32 v218, v199 offset:12484
	ds_write_b32 v218, v200 offset:12488
	ds_write_b32 v218, v201 offset:12492
	v_mad_u32_u24 v224, v227, s35, v228
	s_waitcnt lgkmcnt(0)
	s_barrier
	ds_read2_b32 v[186:187], v219 offset1:65
	ds_read2_b32 v[188:189], v219 offset0:130 offset1:195
	ds_read2_b32 v[190:191], v220 offset0:4 offset1:69
	ds_read2_b32 v[192:193], v220 offset0:134 offset1:199
	ds_read2_b32 v[194:195], v221 offset1:65
	ds_read2_b32 v[196:197], v221 offset0:130 offset1:195
	ds_read2_b32 v[198:199], v222 offset0:4 offset1:69
	ds_read2_b32 v[200:201], v222 offset0:134 offset1:199
	s_add_u32 s96, s52, s32
	s_addc_u32 s97, s53, 0
	s_waitcnt lgkmcnt(0)
	s_barrier
	v_cvt_pk_bf16_f32 v186, v186, v187
	v_cvt_pk_bf16_f32 v187, v188, v189
	v_cvt_pk_bf16_f32 v188, v190, v191
	v_cvt_pk_bf16_f32 v189, v192, v193
	v_cvt_pk_bf16_f32 v194, v194, v195
	v_cvt_pk_bf16_f32 v195, v196, v197
	v_cvt_pk_bf16_f32 v196, v198, v199
	v_cvt_pk_bf16_f32 v197, v200, v201
	global_store_dwordx4 v224, v[186:189], s[52:53]
	global_store_dwordx4 v224, v[194:197], s[96:97]
	s_cmp_ge_u32 s100, s66
	s_cbranch_scc1 .Lwc0_tail3
	s_cmpk_ge_u32 s100, 0x900
	s_cbranch_scc1 .Lwc0_t3_8
	s_cmpk_ge_u32 s100, 0x380
	s_cbranch_scc1 .Lwc0_t2_8
	s_cmpk_ge_u32 s100, 0x280
	s_cbranch_scc1 .Lwc0_t1_8
	s_movk_i32 s41, 0x78
	s_sub_u32 s99, s100, 0
	s_mul_i32 s44, s99, 0x66667
	s_lshr_b32 s44, s44, 24
	s_mul_i32 s36, s44, 40
	s_sub_u32 s99, s99, s36
	s_mul_i32 s38, s44, 0xa0000
	s_lshl_b32 s36, s99, 8
	s_add_u32 s38, s38, s36
	s_add_u32 s38, s38, 0x0
	s_lshl_b32 s36, s99, 6
	s_mov_b32 s32, 0x10000
	s_mul_i32 s36, s36, 0x800
	s_lshl_b32 s44, s44, 7
	s_add_u32 s36, s36, s44
	s_add_u32 s36, s36, 0x0
	s_mov_b32 s37, 0x28000
	s_movk_i32 s44, 0x800
	s_mov_b32 s99, 0x2800
	s_branch .Lwc0_tj_8

.Lwc0_tj_8:
	s_load_dwordx2 s[2:3], s[0:1], s41
	s_add_u32 s52, s4, s36
	s_addc_u32 s53, s5, 0
	v_mad_u32_u24 v223, v225, s99, v226
	v_writelane_b32 v229, s52, 20
	v_writelane_b32 v229, s53, 21
	v_writelane_b32 v229, s32, 22
	v_writelane_b32 v229, s44, 23
	s_add_u32 s100, s100, s67
	s_waitcnt lgkmcnt(0)
	s_add_u32 s38, s2, s38
	s_addc_u32 s39, s3, 0
	global_load_dwordx4 v[186:189], v223, s[38:39] nt
	s_add_u32 s38, s38, s37
	s_addc_u32 s39, s39, 0
	global_load_dwordx4 v[190:193], v223, s[38:39] nt
	s_add_u32 s38, s38, s37
	s_addc_u32 s39, s39, 0
	global_load_dwordx4 v[194:197], v223, s[38:39] nt
	s_add_u32 s38, s38, s37
	s_addc_u32 s39, s39, 0
	global_load_dwordx4 v[198:201], v223, s[38:39] nt
	s_branch .Lwc0_loop
.Lwc0_tail0:
	s_waitcnt vmcnt(0)
	v_readlane_b32 s52, v229, 12
	v_readlane_b32 s53, v229, 13
	v_readlane_b32 s32, v229, 14
	v_readlane_b32 s35, v229, 15
	ds_write_b32 v218, v154 offset:0
	ds_write_b32 v218, v155 offset:4
	ds_write_b32 v218, v156 offset:8
	ds_write_b32 v218, v157 offset:12
	ds_write_b32 v218, v158 offset:4160
	ds_write_b32 v218, v159 offset:4164
	ds_write_b32 v218, v160 offset:4168
	ds_write_b32 v218, v161 offset:4172
	ds_write_b32 v218, v162 offset:8320
	ds_write_b32 v218, v163 offset:8324
	ds_write_b32 v218, v164 offset:8328
	ds_write_b32 v218, v165 offset:8332
	ds_write_b32 v218, v166 offset:12480
	ds_write_b32 v218, v167 offset:12484
	ds_write_b32 v218, v168 offset:12488
	ds_write_b32 v218, v169 offset:12492
	v_mad_u32_u24 v224, v227, s35, v228
	s_waitcnt lgkmcnt(0)
	s_barrier
	ds_read2_b32 v[154:155], v219 offset1:65
	ds_read2_b32 v[156:157], v219 offset0:130 offset1:195
	ds_read2_b32 v[158:159], v220 offset0:4 offset1:69
	ds_read2_b32 v[160:161], v220 offset0:134 offset1:199
	ds_read2_b32 v[162:163], v221 offset1:65
	ds_read2_b32 v[164:165], v221 offset0:130 offset1:195
	ds_read2_b32 v[166:167], v222 offset0:4 offset1:69
	ds_read2_b32 v[168:169], v222 offset0:134 offset1:199
	s_add_u32 s96, s52, s32
	s_addc_u32 s97, s53, 0
	s_waitcnt lgkmcnt(0)
	s_barrier
	v_cvt_pk_bf16_f32 v154, v154, v155
	v_cvt_pk_bf16_f32 v155, v156, v157
	v_cvt_pk_bf16_f32 v156, v158, v159
	v_cvt_pk_bf16_f32 v157, v160, v161
	v_cvt_pk_bf16_f32 v162, v162, v163
	v_cvt_pk_bf16_f32 v163, v164, v165
	v_cvt_pk_bf16_f32 v164, v166, v167
	v_cvt_pk_bf16_f32 v165, v168, v169
	global_store_dwordx4 v224, v[154:157], s[52:53]
	global_store_dwordx4 v224, v[162:165], s[96:97]
	v_readlane_b32 s52, v229, 16
	v_readlane_b32 s53, v229, 17
	v_readlane_b32 s32, v229, 18
	v_readlane_b32 s35, v229, 19
	ds_write_b32 v218, v170 offset:0
	ds_write_b32 v218, v171 offset:4
	ds_write_b32 v218, v172 offset:8
	ds_write_b32 v218, v173 offset:12
	ds_write_b32 v218, v174 offset:4160
	ds_write_b32 v218, v175 offset:4164
	ds_write_b32 v218, v176 offset:4168
	ds_write_b32 v218, v177 offset:4172
	ds_write_b32 v218, v178 offset:8320
	ds_write_b32 v218, v179 offset:8324
	ds_write_b32 v218, v180 offset:8328
	ds_write_b32 v218, v181 offset:8332
	ds_write_b32 v218, v182 offset:12480
	ds_write_b32 v218, v183 offset:12484
	ds_write_b32 v218, v184 offset:12488
	ds_write_b32 v218, v185 offset:12492
	v_mad_u32_u24 v224, v227, s35, v228
	s_waitcnt lgkmcnt(0)
	s_barrier
	ds_read2_b32 v[170:171], v219 offset1:65
	ds_read2_b32 v[172:173], v219 offset0:130 offset1:195
	ds_read2_b32 v[174:175], v220 offset0:4 offset1:69
	ds_read2_b32 v[176:177], v220 offset0:134 offset1:199
	ds_read2_b32 v[178:179], v221 offset1:65
	ds_read2_b32 v[180:181], v221 offset0:130 offset1:195
	ds_read2_b32 v[182:183], v222 offset0:4 offset1:69
	ds_read2_b32 v[184:185], v222 offset0:134 offset1:199
	s_add_u32 s96, s52, s32
	s_addc_u32 s97, s53, 0
	s_waitcnt lgkmcnt(0)
	s_barrier
	v_cvt_pk_bf16_f32 v170, v170, v171
	v_cvt_pk_bf16_f32 v171, v172, v173
	v_cvt_pk_bf16_f32 v172, v174, v175
	v_cvt_pk_bf16_f32 v173, v176, v177
	v_cvt_pk_bf16_f32 v178, v178, v179
	v_cvt_pk_bf16_f32 v179, v180, v181
	v_cvt_pk_bf16_f32 v180, v182, v183
	v_cvt_pk_bf16_f32 v181, v184, v185
	global_store_dwordx4 v224, v[170:173], s[52:53]
	global_store_dwordx4 v224, v[178:181], s[96:97]
	v_readlane_b32 s52, v229, 20
	v_readlane_b32 s53, v229, 21
	v_readlane_b32 s32, v229, 22
	v_readlane_b32 s35, v229, 23
	ds_write_b32 v218, v186 offset:0
	ds_write_b32 v218, v187 offset:4
	ds_write_b32 v218, v188 offset:8
	ds_write_b32 v218, v189 offset:12
	ds_write_b32 v218, v190 offset:4160
	ds_write_b32 v218, v191 offset:4164
	ds_write_b32 v218, v192 offset:4168
	ds_write_b32 v218, v193 offset:4172
	ds_write_b32 v218, v194 offset:8320
	ds_write_b32 v218, v195 offset:8324
	ds_write_b32 v218, v196 offset:8328
	ds_write_b32 v218, v197 offset:8332
	ds_write_b32 v218, v198 offset:12480
	ds_write_b32 v218, v199 offset:12484
	ds_write_b32 v218, v200 offset:12488
	ds_write_b32 v218, v201 offset:12492
	v_mad_u32_u24 v224, v227, s35, v228
	s_waitcnt lgkmcnt(0)
	s_barrier
	ds_read2_b32 v[186:187], v219 offset1:65
	ds_read2_b32 v[188:189], v219 offset0:130 offset1:195
	ds_read2_b32 v[190:191], v220 offset0:4 offset1:69
	ds_read2_b32 v[192:193], v220 offset0:134 offset1:199
	ds_read2_b32 v[194:195], v221 offset1:65
	ds_read2_b32 v[196:197], v221 offset0:130 offset1:195
	ds_read2_b32 v[198:199], v222 offset0:4 offset1:69
	ds_read2_b32 v[200:201], v222 offset0:134 offset1:199
	s_add_u32 s96, s52, s32
	s_addc_u32 s97, s53, 0
	s_waitcnt lgkmcnt(0)
	s_barrier
	v_cvt_pk_bf16_f32 v186, v186, v187
	v_cvt_pk_bf16_f32 v187, v188, v189
	v_cvt_pk_bf16_f32 v188, v190, v191
	v_cvt_pk_bf16_f32 v189, v192, v193
	v_cvt_pk_bf16_f32 v194, v194, v195
	v_cvt_pk_bf16_f32 v195, v196, v197
	v_cvt_pk_bf16_f32 v196, v198, v199
	v_cvt_pk_bf16_f32 v197, v200, v201
	global_store_dwordx4 v224, v[186:189], s[52:53]
	global_store_dwordx4 v224, v[194:197], s[96:97]
	s_branch .Lwc0_done
.Lwc0_tail1:
	s_waitcnt vmcnt(0)
	v_readlane_b32 s52, v229, 16
	v_readlane_b32 s53, v229, 17
	v_readlane_b32 s32, v229, 18
	v_readlane_b32 s35, v229, 19
	ds_write_b32 v218, v170 offset:0
	ds_write_b32 v218, v171 offset:4
	ds_write_b32 v218, v172 offset:8
	ds_write_b32 v218, v173 offset:12
	ds_write_b32 v218, v174 offset:4160
	ds_write_b32 v218, v175 offset:4164
	ds_write_b32 v218, v176 offset:4168
	ds_write_b32 v218, v177 offset:4172
	ds_write_b32 v218, v178 offset:8320
	ds_write_b32 v218, v179 offset:8324
	ds_write_b32 v218, v180 offset:8328
	ds_write_b32 v218, v181 offset:8332
	ds_write_b32 v218, v182 offset:12480
	ds_write_b32 v218, v183 offset:12484
	ds_write_b32 v218, v184 offset:12488
	ds_write_b32 v218, v185 offset:12492
	v_mad_u32_u24 v224, v227, s35, v228
	s_waitcnt lgkmcnt(0)
	s_barrier
	ds_read2_b32 v[170:171], v219 offset1:65
	ds_read2_b32 v[172:173], v219 offset0:130 offset1:195
	ds_read2_b32 v[174:175], v220 offset0:4 offset1:69
	ds_read2_b32 v[176:177], v220 offset0:134 offset1:199
	ds_read2_b32 v[178:179], v221 offset1:65
	ds_read2_b32 v[180:181], v221 offset0:130 offset1:195
	ds_read2_b32 v[182:183], v222 offset0:4 offset1:69
	ds_read2_b32 v[184:185], v222 offset0:134 offset1:199
	s_add_u32 s96, s52, s32
	s_addc_u32 s97, s53, 0
	s_waitcnt lgkmcnt(0)
	s_barrier
	v_cvt_pk_bf16_f32 v170, v170, v171
	v_cvt_pk_bf16_f32 v171, v172, v173
	v_cvt_pk_bf16_f32 v172, v174, v175
	v_cvt_pk_bf16_f32 v173, v176, v177
	v_cvt_pk_bf16_f32 v178, v178, v179
	v_cvt_pk_bf16_f32 v179, v180, v181
	v_cvt_pk_bf16_f32 v180, v182, v183
	v_cvt_pk_bf16_f32 v181, v184, v185
	global_store_dwordx4 v224, v[170:173], s[52:53]
	global_store_dwordx4 v224, v[178:181], s[96:97]
	v_readlane_b32 s52, v229, 20
	v_readlane_b32 s53, v229, 21
	v_readlane_b32 s32, v229, 22
	v_readlane_b32 s35, v229, 23
	ds_write_b32 v218, v186 offset:0
	ds_write_b32 v218, v187 offset:4
	ds_write_b32 v218, v188 offset:8
	ds_write_b32 v218, v189 offset:12
	ds_write_b32 v218, v190 offset:4160
	ds_write_b32 v218, v191 offset:4164
	ds_write_b32 v218, v192 offset:4168
	ds_write_b32 v218, v193 offset:4172
	ds_write_b32 v218, v194 offset:8320
	ds_write_b32 v218, v195 offset:8324
	ds_write_b32 v218, v196 offset:8328
	ds_write_b32 v218, v197 offset:8332
	ds_write_b32 v218, v198 offset:12480
	ds_write_b32 v218, v199 offset:12484
	ds_write_b32 v218, v200 offset:12488
	ds_write_b32 v218, v201 offset:12492
	v_mad_u32_u24 v224, v227, s35, v228
	s_waitcnt lgkmcnt(0)
	s_barrier
	ds_read2_b32 v[186:187], v219 offset1:65
	ds_read2_b32 v[188:189], v219 offset0:130 offset1:195
	ds_read2_b32 v[190:191], v220 offset0:4 offset1:69
	ds_read2_b32 v[192:193], v220 offset0:134 offset1:199
	ds_read2_b32 v[194:195], v221 offset1:65
	ds_read2_b32 v[196:197], v221 offset0:130 offset1:195
	ds_read2_b32 v[198:199], v222 offset0:4 offset1:69
	ds_read2_b32 v[200:201], v222 offset0:134 offset1:199
	s_add_u32 s96, s52, s32
	s_addc_u32 s97, s53, 0
	s_waitcnt lgkmcnt(0)
	s_barrier
	v_cvt_pk_bf16_f32 v186, v186, v187
	v_cvt_pk_bf16_f32 v187, v188, v189
	v_cvt_pk_bf16_f32 v188, v190, v191
	v_cvt_pk_bf16_f32 v189, v192, v193
	v_cvt_pk_bf16_f32 v194, v194, v195
	v_cvt_pk_bf16_f32 v195, v196, v197
	v_cvt_pk_bf16_f32 v196, v198, v199
	v_cvt_pk_bf16_f32 v197, v200, v201
	global_store_dwordx4 v224, v[186:189], s[52:53]
	global_store_dwordx4 v224, v[194:197], s[96:97]
	v_readlane_b32 s52, v229, 8
	v_readlane_b32 s53, v229, 9
	v_readlane_b32 s32, v229, 10
	v_readlane_b32 s35, v229, 11
	ds_write_b32 v218, v138 offset:0
	ds_write_b32 v218, v139 offset:4
	ds_write_b32 v218, v140 offset:8
	ds_write_b32 v218, v141 offset:12
	ds_write_b32 v218, v142 offset:4160
	ds_write_b32 v218, v143 offset:4164
	ds_write_b32 v218, v144 offset:4168
	ds_write_b32 v218, v145 offset:4172
	ds_write_b32 v218, v146 offset:8320
	ds_write_b32 v218, v147 offset:8324
	ds_write_b32 v218, v148 offset:8328
	ds_write_b32 v218, v149 offset:8332
	ds_write_b32 v218, v150 offset:12480
	ds_write_b32 v218, v151 offset:12484
	ds_write_b32 v218, v152 offset:12488
	ds_write_b32 v218, v153 offset:12492
	v_mad_u32_u24 v224, v227, s35, v228
	s_waitcnt lgkmcnt(0)
	s_barrier
	ds_read2_b32 v[138:139], v219 offset1:65
	ds_read2_b32 v[140:141], v219 offset0:130 offset1:195
	ds_read2_b32 v[142:143], v220 offset0:4 offset1:69
	ds_read2_b32 v[144:145], v220 offset0:134 offset1:199
	ds_read2_b32 v[146:147], v221 offset1:65
	ds_read2_b32 v[148:149], v221 offset0:130 offset1:195
	ds_read2_b32 v[150:151], v222 offset0:4 offset1:69
	ds_read2_b32 v[152:153], v222 offset0:134 offset1:199
	s_add_u32 s96, s52, s32
	s_addc_u32 s97, s53, 0
	s_waitcnt lgkmcnt(0)
	s_barrier
	v_cvt_pk_bf16_f32 v138, v138, v139
	v_cvt_pk_bf16_f32 v139, v140, v141
	v_cvt_pk_bf16_f32 v140, v142, v143
	v_cvt_pk_bf16_f32 v141, v144, v145
	v_cvt_pk_bf16_f32 v146, v146, v147
	v_cvt_pk_bf16_f32 v147, v148, v149
	v_cvt_pk_bf16_f32 v148, v150, v151
	v_cvt_pk_bf16_f32 v149, v152, v153
	global_store_dwordx4 v224, v[138:141], s[52:53]
	global_store_dwordx4 v224, v[146:149], s[96:97]
	s_branch .Lwc0_done
.Lwc0_tail2:
	s_waitcnt vmcnt(0)
	v_readlane_b32 s52, v229, 20
	v_readlane_b32 s53, v229, 21
	v_readlane_b32 s32, v229, 22
	v_readlane_b32 s35, v229, 23
	ds_write_b32 v218, v186 offset:0
	ds_write_b32 v218, v187 offset:4
	ds_write_b32 v218, v188 offset:8
	ds_write_b32 v218, v189 offset:12
	ds_write_b32 v218, v190 offset:4160
	ds_write_b32 v218, v191 offset:4164
	ds_write_b32 v218, v192 offset:4168
	ds_write_b32 v218, v193 offset:4172
	ds_write_b32 v218, v194 offset:8320
	ds_write_b32 v218, v195 offset:8324
	ds_write_b32 v218, v196 offset:8328
	ds_write_b32 v218, v197 offset:8332
	ds_write_b32 v218, v198 offset:12480
	ds_write_b32 v218, v199 offset:12484
	ds_write_b32 v218, v200 offset:12488
	ds_write_b32 v218, v201 offset:12492
	v_mad_u32_u24 v224, v227, s35, v228
	s_waitcnt lgkmcnt(0)
	s_barrier
	ds_read2_b32 v[186:187], v219 offset1:65
	ds_read2_b32 v[188:189], v219 offset0:130 offset1:195
	ds_read2_b32 v[190:191], v220 offset0:4 offset1:69
	ds_read2_b32 v[192:193], v220 offset0:134 offset1:199
	ds_read2_b32 v[194:195], v221 offset1:65
	ds_read2_b32 v[196:197], v221 offset0:130 offset1:195
	ds_read2_b32 v[198:199], v222 offset0:4 offset1:69
	ds_read2_b32 v[200:201], v222 offset0:134 offset1:199
	s_add_u32 s96, s52, s32
	s_addc_u32 s97, s53, 0
	s_waitcnt lgkmcnt(0)
	s_barrier
	v_cvt_pk_bf16_f32 v186, v186, v187
	v_cvt_pk_bf16_f32 v187, v188, v189
	v_cvt_pk_bf16_f32 v188, v190, v191
	v_cvt_pk_bf16_f32 v189, v192, v193
	v_cvt_pk_bf16_f32 v194, v194, v195
	v_cvt_pk_bf16_f32 v195, v196, v197
	v_cvt_pk_bf16_f32 v196, v198, v199
	v_cvt_pk_bf16_f32 v197, v200, v201
	global_store_dwordx4 v224, v[186:189], s[52:53]
	global_store_dwordx4 v224, v[194:197], s[96:97]
	v_readlane_b32 s52, v229, 8
	v_readlane_b32 s53, v229, 9
	v_readlane_b32 s32, v229, 10
	v_readlane_b32 s35, v229, 11
	ds_write_b32 v218, v138 offset:0
	ds_write_b32 v218, v139 offset:4
	ds_write_b32 v218, v140 offset:8
	ds_write_b32 v218, v141 offset:12
	ds_write_b32 v218, v142 offset:4160
	ds_write_b32 v218, v143 offset:4164
	ds_write_b32 v218, v144 offset:4168
	ds_write_b32 v218, v145 offset:4172
	ds_write_b32 v218, v146 offset:8320
	ds_write_b32 v218, v147 offset:8324
	ds_write_b32 v218, v148 offset:8328
	ds_write_b32 v218, v149 offset:8332
	ds_write_b32 v218, v150 offset:12480
	ds_write_b32 v218, v151 offset:12484
	ds_write_b32 v218, v152 offset:12488
	ds_write_b32 v218, v153 offset:12492
	v_mad_u32_u24 v224, v227, s35, v228
	s_waitcnt lgkmcnt(0)
	s_barrier
	ds_read2_b32 v[138:139], v219 offset1:65
	ds_read2_b32 v[140:141], v219 offset0:130 offset1:195
	ds_read2_b32 v[142:143], v220 offset0:4 offset1:69
	ds_read2_b32 v[144:145], v220 offset0:134 offset1:199
	ds_read2_b32 v[146:147], v221 offset1:65
	ds_read2_b32 v[148:149], v221 offset0:130 offset1:195
	ds_read2_b32 v[150:151], v222 offset0:4 offset1:69
	ds_read2_b32 v[152:153], v222 offset0:134 offset1:199
	s_add_u32 s96, s52, s32
	s_addc_u32 s97, s53, 0
	s_waitcnt lgkmcnt(0)
	s_barrier
	v_cvt_pk_bf16_f32 v138, v138, v139
	v_cvt_pk_bf16_f32 v139, v140, v141
	v_cvt_pk_bf16_f32 v140, v142, v143
	v_cvt_pk_bf16_f32 v141, v144, v145
	v_cvt_pk_bf16_f32 v146, v146, v147
	v_cvt_pk_bf16_f32 v147, v148, v149
	v_cvt_pk_bf16_f32 v148, v150, v151
	v_cvt_pk_bf16_f32 v149, v152, v153
	global_store_dwordx4 v224, v[138:141], s[52:53]
	global_store_dwordx4 v224, v[146:149], s[96:97]
	v_readlane_b32 s52, v229, 12
	v_readlane_b32 s53, v229, 13
	v_readlane_b32 s32, v229, 14
	v_readlane_b32 s35, v229, 15
	ds_write_b32 v218, v154 offset:0
	ds_write_b32 v218, v155 offset:4
	ds_write_b32 v218, v156 offset:8
	ds_write_b32 v218, v157 offset:12
	ds_write_b32 v218, v158 offset:4160
	ds_write_b32 v218, v159 offset:4164
	ds_write_b32 v218, v160 offset:4168
	ds_write_b32 v218, v161 offset:4172
	ds_write_b32 v218, v162 offset:8320
	ds_write_b32 v218, v163 offset:8324
	ds_write_b32 v218, v164 offset:8328
	ds_write_b32 v218, v165 offset:8332
	ds_write_b32 v218, v166 offset:12480
	ds_write_b32 v218, v167 offset:12484
	ds_write_b32 v218, v168 offset:12488
	ds_write_b32 v218, v169 offset:12492
	v_mad_u32_u24 v224, v227, s35, v228
	s_waitcnt lgkmcnt(0)
	s_barrier
	ds_read2_b32 v[154:155], v219 offset1:65
	ds_read2_b32 v[156:157], v219 offset0:130 offset1:195
	ds_read2_b32 v[158:159], v220 offset0:4 offset1:69
	ds_read2_b32 v[160:161], v220 offset0:134 offset1:199
	ds_read2_b32 v[162:163], v221 offset1:65
	ds_read2_b32 v[164:165], v221 offset0:130 offset1:195
	ds_read2_b32 v[166:167], v222 offset0:4 offset1:69
	ds_read2_b32 v[168:169], v222 offset0:134 offset1:199
	s_add_u32 s96, s52, s32
	s_addc_u32 s97, s53, 0
	s_waitcnt lgkmcnt(0)
	s_barrier
	v_cvt_pk_bf16_f32 v154, v154, v155
	v_cvt_pk_bf16_f32 v155, v156, v157
	v_cvt_pk_bf16_f32 v156, v158, v159
	v_cvt_pk_bf16_f32 v157, v160, v161
	v_cvt_pk_bf16_f32 v162, v162, v163
	v_cvt_pk_bf16_f32 v163, v164, v165
	v_cvt_pk_bf16_f32 v164, v166, v167
	v_cvt_pk_bf16_f32 v165, v168, v169
	global_store_dwordx4 v224, v[154:157], s[52:53]
	global_store_dwordx4 v224, v[162:165], s[96:97]
	s_branch .Lwc0_done

.Lwcm0_tj_3:
	s_load_dwordx2 s[8:9], s[0:1], s14
	s_add_u32 s20, s12, s36
	s_addc_u32 s21, s13, 0
	v_mad_u32_u24 v231, v233, s99, v234
	v_writelane_b32 v237, s20, 16
	v_writelane_b32 v237, s21, 17
	v_writelane_b32 v237, s32, 18
	v_writelane_b32 v237, s44, 19
	s_add_u32 s100, s100, s23
	s_waitcnt lgkmcnt(0)
	s_add_u32 s38, s8, s38
	s_addc_u32 s39, s9, 0
	global_load_dwordx4 v[178:181], v231, s[38:39] nt
	s_add_u32 s38, s38, s37
	s_addc_u32 s39, s39, 0
	global_load_dwordx4 v[182:185], v231, s[38:39] nt
	s_add_u32 s38, s38, s37
	s_addc_u32 s39, s39, 0
	global_load_dwordx4 v[186:189], v231, s[38:39] nt
	s_add_u32 s38, s38, s37
	s_addc_u32 s39, s39, 0
	global_load_dwordx4 v[190:193], v231, s[38:39] nt
	s_cmp_ge_u32 s100, s22
	s_cbranch_scc1 .Lwcm0_p3
	s_cmpk_ge_u32 s100, 0x900
	s_cbranch_scc1 .Lwcm0_t3_4
	s_cmpk_ge_u32 s100, 0x380
	s_cbranch_scc1 .Lwcm0_t2_4
	s_cmpk_ge_u32 s100, 0x280
	s_cbranch_scc1 .Lwcm0_t1_4
	s_movk_i32 s14, 0x78
	s_sub_u32 s99, s100, 0
	s_mul_i32 s44, s99, 0x66667
	s_lshr_b32 s44, s44, 24
	s_mul_i32 s36, s44, 40
	s_sub_u32 s99, s99, s36
	s_mul_i32 s38, s44, 0xa0000
	s_lshl_b32 s36, s99, 8
	s_add_u32 s38, s38, s36
	s_add_u32 s38, s38, 0x0
	s_lshl_b32 s36, s99, 6
	s_mov_b32 s32, 0x10000
	s_mul_i32 s36, s36, 0x800
	s_lshl_b32 s44, s44, 7
	s_add_u32 s36, s36, s44
	s_add_u32 s36, s36, 0x0
	s_mov_b32 s37, 0x28000
	s_movk_i32 s44, 0x800
	s_mov_b32 s99, 0x2800
	s_branch .Lwcm0_tj_4

.Lwcm0_tj_4:
	s_load_dwordx2 s[8:9], s[0:1], s14
	s_add_u32 s20, s12, s36
	s_addc_u32 s21, s13, 0
	v_mad_u32_u24 v231, v233, s99, v234
	v_writelane_b32 v237, s20, 20
	v_writelane_b32 v237, s21, 21
	v_writelane_b32 v237, s32, 22
	v_writelane_b32 v237, s44, 23
	s_add_u32 s100, s100, s23
	s_waitcnt lgkmcnt(0)
	s_add_u32 s38, s8, s38
	s_addc_u32 s39, s9, 0
	global_load_dwordx4 v[194:197], v231, s[38:39] nt
	s_add_u32 s38, s38, s37
	s_addc_u32 s39, s39, 0
	global_load_dwordx4 v[198:201], v231, s[38:39] nt
	s_add_u32 s38, s38, s37
	s_addc_u32 s39, s39, 0
	global_load_dwordx4 v[202:205], v231, s[38:39] nt
	s_add_u32 s38, s38, s37
	s_addc_u32 s39, s39, 0
	global_load_dwordx4 v[206:209], v231, s[38:39] nt
.Lwcm0_loop:
	s_waitcnt vmcnt(12)
	v_readlane_b32 s20, v237, 8
	v_readlane_b32 s21, v237, 9
	v_readlane_b32 s32, v237, 10
	v_readlane_b32 s35, v237, 11
	ds_write_b32 v226, v146 offset:0
	ds_write_b32 v226, v147 offset:4
	ds_write_b32 v226, v148 offset:8
	ds_write_b32 v226, v149 offset:12
	ds_write_b32 v226, v150 offset:4160
	ds_write_b32 v226, v151 offset:4164
	ds_write_b32 v226, v152 offset:4168
	ds_write_b32 v226, v153 offset:4172
	ds_write_b32 v226, v154 offset:8320
	ds_write_b32 v226, v155 offset:8324
	ds_write_b32 v226, v156 offset:8328
	ds_write_b32 v226, v157 offset:8332
	ds_write_b32 v226, v158 offset:12480
	ds_write_b32 v226, v159 offset:12484
	ds_write_b32 v226, v160 offset:12488
	ds_write_b32 v226, v161 offset:12492
	v_mad_u32_u24 v232, v235, s35, v236
	s_waitcnt lgkmcnt(0)
	s_barrier
	ds_read2_b32 v[146:147], v227 offset1:65
	ds_read2_b32 v[148:149], v227 offset0:130 offset1:195
	ds_read2_b32 v[150:151], v228 offset0:4 offset1:69
	ds_read2_b32 v[152:153], v228 offset0:134 offset1:199
	ds_read2_b32 v[154:155], v229 offset1:65
	ds_read2_b32 v[156:157], v229 offset0:130 offset1:195
	ds_read2_b32 v[158:159], v230 offset0:4 offset1:69
	ds_read2_b32 v[160:161], v230 offset0:134 offset1:199
	s_add_u32 s26, s20, s32
	s_addc_u32 s27, s21, 0
	s_waitcnt lgkmcnt(0)
	s_barrier
	v_cvt_pk_bf16_f32 v146, v146, v147
	v_cvt_pk_bf16_f32 v147, v148, v149
	v_cvt_pk_bf16_f32 v148, v150, v151
	v_cvt_pk_bf16_f32 v149, v152, v153
	v_cvt_pk_bf16_f32 v154, v154, v155
	v_cvt_pk_bf16_f32 v155, v156, v157
	v_cvt_pk_bf16_f32 v156, v158, v159
	v_cvt_pk_bf16_f32 v157, v160, v161
	global_store_dwordx4 v232, v[146:149], s[20:21]
	global_store_dwordx4 v232, v[154:157], s[26:27]
	s_cmp_ge_u32 s100, s22
	s_cbranch_scc1 .Lwcm0_tail0
	s_cmpk_ge_u32 s100, 0x900
	s_cbranch_scc1 .Lwcm0_t3_5
	s_cmpk_ge_u32 s100, 0x380
	s_cbranch_scc1 .Lwcm0_t2_5
	s_cmpk_ge_u32 s100, 0x280
	s_cbranch_scc1 .Lwcm0_t1_5
	s_movk_i32 s14, 0x78
	s_sub_u32 s99, s100, 0
	s_mul_i32 s44, s99, 0x66667
	s_lshr_b32 s44, s44, 24
	s_mul_i32 s36, s44, 40
	s_sub_u32 s99, s99, s36
	s_mul_i32 s38, s44, 0xa0000
	s_lshl_b32 s36, s99, 8
	s_add_u32 s38, s38, s36
	s_add_u32 s38, s38, 0x0
	s_lshl_b32 s36, s99, 6
	s_mov_b32 s32, 0x10000
	s_mul_i32 s36, s36, 0x800
	s_lshl_b32 s44, s44, 7
	s_add_u32 s36, s36, s44
	s_add_u32 s36, s36, 0x0
	s_mov_b32 s37, 0x28000
	s_movk_i32 s44, 0x800
	s_mov_b32 s99, 0x2800
	s_branch .Lwcm0_tj_5

.Lwcm0_tj_5:
	s_load_dwordx2 s[8:9], s[0:1], s14
	s_add_u32 s20, s12, s36
	s_addc_u32 s21, s13, 0
	v_mad_u32_u24 v231, v233, s99, v234
	v_writelane_b32 v237, s20, 8
	v_writelane_b32 v237, s21, 9
	v_writelane_b32 v237, s32, 10
	v_writelane_b32 v237, s44, 11
	s_add_u32 s100, s100, s23
	s_waitcnt lgkmcnt(0)
	s_add_u32 s38, s8, s38
	s_addc_u32 s39, s9, 0
	global_load_dwordx4 v[146:149], v231, s[38:39] nt
	s_add_u32 s38, s38, s37
	s_addc_u32 s39, s39, 0
	global_load_dwordx4 v[150:153], v231, s[38:39] nt
	s_add_u32 s38, s38, s37
	s_addc_u32 s39, s39, 0
	global_load_dwordx4 v[154:157], v231, s[38:39] nt
	s_add_u32 s38, s38, s37
	s_addc_u32 s39, s39, 0
	global_load_dwordx4 v[158:161], v231, s[38:39] nt
	s_waitcnt vmcnt(12)
	v_readlane_b32 s20, v237, 12
	v_readlane_b32 s21, v237, 13
	v_readlane_b32 s32, v237, 14
	v_readlane_b32 s35, v237, 15
	ds_write_b32 v226, v162 offset:0
	ds_write_b32 v226, v163 offset:4
	ds_write_b32 v226, v164 offset:8
	ds_write_b32 v226, v165 offset:12
	ds_write_b32 v226, v166 offset:4160
	ds_write_b32 v226, v167 offset:4164
	ds_write_b32 v226, v168 offset:4168
	ds_write_b32 v226, v169 offset:4172
	ds_write_b32 v226, v170 offset:8320
	ds_write_b32 v226, v171 offset:8324
	ds_write_b32 v226, v172 offset:8328
	ds_write_b32 v226, v173 offset:8332
	ds_write_b32 v226, v174 offset:12480
	ds_write_b32 v226, v175 offset:12484
	ds_write_b32 v226, v176 offset:12488
	ds_write_b32 v226, v177 offset:12492
	v_mad_u32_u24 v232, v235, s35, v236
	s_waitcnt lgkmcnt(0)
	s_barrier
	ds_read2_b32 v[162:163], v227 offset1:65
	ds_read2_b32 v[164:165], v227 offset0:130 offset1:195
	ds_read2_b32 v[166:167], v228 offset0:4 offset1:69
	ds_read2_b32 v[168:169], v228 offset0:134 offset1:199
	ds_read2_b32 v[170:171], v229 offset1:65
	ds_read2_b32 v[172:173], v229 offset0:130 offset1:195
	ds_read2_b32 v[174:175], v230 offset0:4 offset1:69
	ds_read2_b32 v[176:177], v230 offset0:134 offset1:199
	s_add_u32 s26, s20, s32
	s_addc_u32 s27, s21, 0
	s_waitcnt lgkmcnt(0)
	s_barrier
	v_cvt_pk_bf16_f32 v162, v162, v163
	v_cvt_pk_bf16_f32 v163, v164, v165
	v_cvt_pk_bf16_f32 v164, v166, v167
	v_cvt_pk_bf16_f32 v165, v168, v169
	v_cvt_pk_bf16_f32 v170, v170, v171
	v_cvt_pk_bf16_f32 v171, v172, v173
	v_cvt_pk_bf16_f32 v172, v174, v175
	v_cvt_pk_bf16_f32 v173, v176, v177
	global_store_dwordx4 v232, v[162:165], s[20:21]
	global_store_dwordx4 v232, v[170:173], s[26:27]
	s_cmp_ge_u32 s100, s22
	s_cbranch_scc1 .Lwcm0_tail1
	s_cmpk_ge_u32 s100, 0x900
	s_cbranch_scc1 .Lwcm0_t3_6
	s_cmpk_ge_u32 s100, 0x380
	s_cbranch_scc1 .Lwcm0_t2_6
	s_cmpk_ge_u32 s100, 0x280
	s_cbranch_scc1 .Lwcm0_t1_6
	s_movk_i32 s14, 0x78
	s_sub_u32 s99, s100, 0
	s_mul_i32 s44, s99, 0x66667
	s_lshr_b32 s44, s44, 24
	s_mul_i32 s36, s44, 40
	s_sub_u32 s99, s99, s36
	s_mul_i32 s38, s44, 0xa0000
	s_lshl_b32 s36, s99, 8
	s_add_u32 s38, s38, s36
	s_add_u32 s38, s38, 0x0
	s_lshl_b32 s36, s99, 6
	s_mov_b32 s32, 0x10000
	s_mul_i32 s36, s36, 0x800
	s_lshl_b32 s44, s44, 7
	s_add_u32 s36, s36, s44
	s_add_u32 s36, s36, 0x0
	s_mov_b32 s37, 0x28000
	s_movk_i32 s44, 0x800
	s_mov_b32 s99, 0x2800
	s_branch .Lwcm0_tj_6

.Lwcm0_tj_6:
	s_load_dwordx2 s[8:9], s[0:1], s14
	s_add_u32 s20, s12, s36
	s_addc_u32 s21, s13, 0
	v_mad_u32_u24 v231, v233, s99, v234
	v_writelane_b32 v237, s20, 12
	v_writelane_b32 v237, s21, 13
	v_writelane_b32 v237, s32, 14
	v_writelane_b32 v237, s44, 15
	s_add_u32 s100, s100, s23
	s_waitcnt lgkmcnt(0)
	s_add_u32 s38, s8, s38
	s_addc_u32 s39, s9, 0
	global_load_dwordx4 v[162:165], v231, s[38:39] nt
	s_add_u32 s38, s38, s37
	s_addc_u32 s39, s39, 0
	global_load_dwordx4 v[166:169], v231, s[38:39] nt
	s_add_u32 s38, s38, s37
	s_addc_u32 s39, s39, 0
	global_load_dwordx4 v[170:173], v231, s[38:39] nt
	s_add_u32 s38, s38, s37
	s_addc_u32 s39, s39, 0
	global_load_dwordx4 v[174:177], v231, s[38:39] nt
	s_waitcnt vmcnt(12)
	v_readlane_b32 s20, v237, 16
	v_readlane_b32 s21, v237, 17
	v_readlane_b32 s32, v237, 18
	v_readlane_b32 s35, v237, 19
	ds_write_b32 v226, v178 offset:0
	ds_write_b32 v226, v179 offset:4
	ds_write_b32 v226, v180 offset:8
	ds_write_b32 v226, v181 offset:12
	ds_write_b32 v226, v182 offset:4160
	ds_write_b32 v226, v183 offset:4164
	ds_write_b32 v226, v184 offset:4168
	ds_write_b32 v226, v185 offset:4172
	ds_write_b32 v226, v186 offset:8320
	ds_write_b32 v226, v187 offset:8324
	ds_write_b32 v226, v188 offset:8328
	ds_write_b32 v226, v189 offset:8332
	ds_write_b32 v226, v190 offset:12480
	ds_write_b32 v226, v191 offset:12484
	ds_write_b32 v226, v192 offset:12488
	ds_write_b32 v226, v193 offset:12492
	v_mad_u32_u24 v232, v235, s35, v236
	s_waitcnt lgkmcnt(0)
	s_barrier
	ds_read2_b32 v[178:179], v227 offset1:65
	ds_read2_b32 v[180:181], v227 offset0:130 offset1:195
	ds_read2_b32 v[182:183], v228 offset0:4 offset1:69
	ds_read2_b32 v[184:185], v228 offset0:134 offset1:199
	ds_read2_b32 v[186:187], v229 offset1:65
	ds_read2_b32 v[188:189], v229 offset0:130 offset1:195
	ds_read2_b32 v[190:191], v230 offset0:4 offset1:69
	ds_read2_b32 v[192:193], v230 offset0:134 offset1:199
	s_add_u32 s26, s20, s32
	s_addc_u32 s27, s21, 0
	s_waitcnt lgkmcnt(0)
	s_barrier
	v_cvt_pk_bf16_f32 v178, v178, v179
	v_cvt_pk_bf16_f32 v179, v180, v181
	v_cvt_pk_bf16_f32 v180, v182, v183
	v_cvt_pk_bf16_f32 v181, v184, v185
	v_cvt_pk_bf16_f32 v186, v186, v187
	v_cvt_pk_bf16_f32 v187, v188, v189
	v_cvt_pk_bf16_f32 v188, v190, v191
	v_cvt_pk_bf16_f32 v189, v192, v193
	global_store_dwordx4 v232, v[178:181], s[20:21]
	global_store_dwordx4 v232, v[186:189], s[26:27]
	s_cmp_ge_u32 s100, s22
	s_cbranch_scc1 .Lwcm0_tail2
	s_cmpk_ge_u32 s100, 0x900
	s_cbranch_scc1 .Lwcm0_t3_7
	s_cmpk_ge_u32 s100, 0x380
	s_cbranch_scc1 .Lwcm0_t2_7
	s_cmpk_ge_u32 s100, 0x280
	s_cbranch_scc1 .Lwcm0_t1_7
	s_movk_i32 s14, 0x78
	s_sub_u32 s99, s100, 0
	s_mul_i32 s44, s99, 0x66667
	s_lshr_b32 s44, s44, 24
	s_mul_i32 s36, s44, 40
	s_sub_u32 s99, s99, s36
	s_mul_i32 s38, s44, 0xa0000
	s_lshl_b32 s36, s99, 8
	s_add_u32 s38, s38, s36
	s_add_u32 s38, s38, 0x0
	s_lshl_b32 s36, s99, 6
	s_mov_b32 s32, 0x10000
	s_mul_i32 s36, s36, 0x800
	s_lshl_b32 s44, s44, 7
	s_add_u32 s36, s36, s44
	s_add_u32 s36, s36, 0x0
	s_mov_b32 s37, 0x28000
	s_movk_i32 s44, 0x800
	s_mov_b32 s99, 0x2800
	s_branch .Lwcm0_tj_7

.Lwcm0_tj_7:
	s_load_dwordx2 s[8:9], s[0:1], s14
	s_add_u32 s20, s12, s36
	s_addc_u32 s21, s13, 0
	v_mad_u32_u24 v231, v233, s99, v234
	v_writelane_b32 v237, s20, 16
	v_writelane_b32 v237, s21, 17
	v_writelane_b32 v237, s32, 18
	v_writelane_b32 v237, s44, 19
	s_add_u32 s100, s100, s23
	s_waitcnt lgkmcnt(0)
	s_add_u32 s38, s8, s38
	s_addc_u32 s39, s9, 0
	global_load_dwordx4 v[178:181], v231, s[38:39] nt
	s_add_u32 s38, s38, s37
	s_addc_u32 s39, s39, 0
	global_load_dwordx4 v[182:185], v231, s[38:39] nt
	s_add_u32 s38, s38, s37
	s_addc_u32 s39, s39, 0
	global_load_dwordx4 v[186:189], v231, s[38:39] nt
	s_add_u32 s38, s38, s37
	s_addc_u32 s39, s39, 0
	global_load_dwordx4 v[190:193], v231, s[38:39] nt
	s_waitcnt vmcnt(12)
	v_readlane_b32 s20, v237, 20
	v_readlane_b32 s21, v237, 21
	v_readlane_b32 s32, v237, 22
	v_readlane_b32 s35, v237, 23
	ds_write_b32 v226, v194 offset:0
	ds_write_b32 v226, v195 offset:4
	ds_write_b32 v226, v196 offset:8
	ds_write_b32 v226, v197 offset:12
	ds_write_b32 v226, v198 offset:4160
	ds_write_b32 v226, v199 offset:4164
	ds_write_b32 v226, v200 offset:4168
	ds_write_b32 v226, v201 offset:4172
	ds_write_b32 v226, v202 offset:8320
	ds_write_b32 v226, v203 offset:8324
	ds_write_b32 v226, v204 offset:8328
	ds_write_b32 v226, v205 offset:8332
	ds_write_b32 v226, v206 offset:12480
	ds_write_b32 v226, v207 offset:12484
	ds_write_b32 v226, v208 offset:12488
	ds_write_b32 v226, v209 offset:12492
	v_mad_u32_u24 v232, v235, s35, v236
	s_waitcnt lgkmcnt(0)
	s_barrier
	ds_read2_b32 v[194:195], v227 offset1:65
	ds_read2_b32 v[196:197], v227 offset0:130 offset1:195
	ds_read2_b32 v[198:199], v228 offset0:4 offset1:69
	ds_read2_b32 v[200:201], v228 offset0:134 offset1:199
	ds_read2_b32 v[202:203], v229 offset1:65
	ds_read2_b32 v[204:205], v229 offset0:130 offset1:195
	ds_read2_b32 v[206:207], v230 offset0:4 offset1:69
	ds_read2_b32 v[208:209], v230 offset0:134 offset1:199
	s_add_u32 s26, s20, s32
	s_addc_u32 s27, s21, 0
	s_waitcnt lgkmcnt(0)
	s_barrier
	v_cvt_pk_bf16_f32 v194, v194, v195
	v_cvt_pk_bf16_f32 v195, v196, v197
	v_cvt_pk_bf16_f32 v196, v198, v199
	v_cvt_pk_bf16_f32 v197, v200, v201
	v_cvt_pk_bf16_f32 v202, v202, v203
	v_cvt_pk_bf16_f32 v203, v204, v205
	v_cvt_pk_bf16_f32 v204, v206, v207
	v_cvt_pk_bf16_f32 v205, v208, v209
	global_store_dwordx4 v232, v[194:197], s[20:21]
	global_store_dwordx4 v232, v[202:205], s[26:27]
	s_cmp_ge_u32 s100, s22
	s_cbranch_scc1 .Lwcm0_tail3
	s_cmpk_ge_u32 s100, 0x900
	s_cbranch_scc1 .Lwcm0_t3_8
	s_cmpk_ge_u32 s100, 0x380
	s_cbranch_scc1 .Lwcm0_t2_8
	s_cmpk_ge_u32 s100, 0x280
	s_cbranch_scc1 .Lwcm0_t1_8
	s_movk_i32 s14, 0x78
	s_sub_u32 s99, s100, 0
	s_mul_i32 s44, s99, 0x66667
	s_lshr_b32 s44, s44, 24
	s_mul_i32 s36, s44, 40
	s_sub_u32 s99, s99, s36
	s_mul_i32 s38, s44, 0xa0000
	s_lshl_b32 s36, s99, 8
	s_add_u32 s38, s38, s36
	s_add_u32 s38, s38, 0x0
	s_lshl_b32 s36, s99, 6
	s_mov_b32 s32, 0x10000
	s_mul_i32 s36, s36, 0x800
	s_lshl_b32 s44, s44, 7
	s_add_u32 s36, s36, s44
	s_add_u32 s36, s36, 0x0
	s_mov_b32 s37, 0x28000
	s_movk_i32 s44, 0x800
	s_mov_b32 s99, 0x2800
	s_branch .Lwcm0_tj_8

.Lwcm0_tj_8:
	s_load_dwordx2 s[8:9], s[0:1], s14
	s_add_u32 s20, s12, s36
	s_addc_u32 s21, s13, 0
	v_mad_u32_u24 v231, v233, s99, v234
	v_writelane_b32 v237, s20, 20
	v_writelane_b32 v237, s21, 21
	v_writelane_b32 v237, s32, 22
	v_writelane_b32 v237, s44, 23
	s_add_u32 s100, s100, s23
	s_waitcnt lgkmcnt(0)
	s_add_u32 s38, s8, s38
	s_addc_u32 s39, s9, 0
	global_load_dwordx4 v[194:197], v231, s[38:39] nt
	s_add_u32 s38, s38, s37
	s_addc_u32 s39, s39, 0
	global_load_dwordx4 v[198:201], v231, s[38:39] nt
	s_add_u32 s38, s38, s37
	s_addc_u32 s39, s39, 0
	global_load_dwordx4 v[202:205], v231, s[38:39] nt
	s_add_u32 s38, s38, s37
	s_addc_u32 s39, s39, 0
	global_load_dwordx4 v[206:209], v231, s[38:39] nt
	s_branch .Lwcm0_loop
.Lwcm0_tail0:
	s_waitcnt vmcnt(0)
	v_readlane_b32 s20, v237, 12
	v_readlane_b32 s21, v237, 13
	v_readlane_b32 s32, v237, 14
	v_readlane_b32 s35, v237, 15
	ds_write_b32 v226, v162 offset:0
	ds_write_b32 v226, v163 offset:4
	ds_write_b32 v226, v164 offset:8
	ds_write_b32 v226, v165 offset:12
	ds_write_b32 v226, v166 offset:4160
	ds_write_b32 v226, v167 offset:4164
	ds_write_b32 v226, v168 offset:4168
	ds_write_b32 v226, v169 offset:4172
	ds_write_b32 v226, v170 offset:8320
	ds_write_b32 v226, v171 offset:8324
	ds_write_b32 v226, v172 offset:8328
	ds_write_b32 v226, v173 offset:8332
	ds_write_b32 v226, v174 offset:12480
	ds_write_b32 v226, v175 offset:12484
	ds_write_b32 v226, v176 offset:12488
	ds_write_b32 v226, v177 offset:12492
	v_mad_u32_u24 v232, v235, s35, v236
	s_waitcnt lgkmcnt(0)
	s_barrier
	ds_read2_b32 v[162:163], v227 offset1:65
	ds_read2_b32 v[164:165], v227 offset0:130 offset1:195
	ds_read2_b32 v[166:167], v228 offset0:4 offset1:69
	ds_read2_b32 v[168:169], v228 offset0:134 offset1:199
	ds_read2_b32 v[170:171], v229 offset1:65
	ds_read2_b32 v[172:173], v229 offset0:130 offset1:195
	ds_read2_b32 v[174:175], v230 offset0:4 offset1:69
	ds_read2_b32 v[176:177], v230 offset0:134 offset1:199
	s_add_u32 s26, s20, s32
	s_addc_u32 s27, s21, 0
	s_waitcnt lgkmcnt(0)
	s_barrier
	v_cvt_pk_bf16_f32 v162, v162, v163
	v_cvt_pk_bf16_f32 v163, v164, v165
	v_cvt_pk_bf16_f32 v164, v166, v167
	v_cvt_pk_bf16_f32 v165, v168, v169
	v_cvt_pk_bf16_f32 v170, v170, v171
	v_cvt_pk_bf16_f32 v171, v172, v173
	v_cvt_pk_bf16_f32 v172, v174, v175
	v_cvt_pk_bf16_f32 v173, v176, v177
	global_store_dwordx4 v232, v[162:165], s[20:21]
	global_store_dwordx4 v232, v[170:173], s[26:27]
	v_readlane_b32 s20, v237, 16
	v_readlane_b32 s21, v237, 17
	v_readlane_b32 s32, v237, 18
	v_readlane_b32 s35, v237, 19
	ds_write_b32 v226, v178 offset:0
	ds_write_b32 v226, v179 offset:4
	ds_write_b32 v226, v180 offset:8
	ds_write_b32 v226, v181 offset:12
	ds_write_b32 v226, v182 offset:4160
	ds_write_b32 v226, v183 offset:4164
	ds_write_b32 v226, v184 offset:4168
	ds_write_b32 v226, v185 offset:4172
	ds_write_b32 v226, v186 offset:8320
	ds_write_b32 v226, v187 offset:8324
	ds_write_b32 v226, v188 offset:8328
	ds_write_b32 v226, v189 offset:8332
	ds_write_b32 v226, v190 offset:12480
	ds_write_b32 v226, v191 offset:12484
	ds_write_b32 v226, v192 offset:12488
	ds_write_b32 v226, v193 offset:12492
	v_mad_u32_u24 v232, v235, s35, v236
	s_waitcnt lgkmcnt(0)
	s_barrier
	ds_read2_b32 v[178:179], v227 offset1:65
	ds_read2_b32 v[180:181], v227 offset0:130 offset1:195
	ds_read2_b32 v[182:183], v228 offset0:4 offset1:69
	ds_read2_b32 v[184:185], v228 offset0:134 offset1:199
	ds_read2_b32 v[186:187], v229 offset1:65
	ds_read2_b32 v[188:189], v229 offset0:130 offset1:195
	ds_read2_b32 v[190:191], v230 offset0:4 offset1:69
	ds_read2_b32 v[192:193], v230 offset0:134 offset1:199
	s_add_u32 s26, s20, s32
	s_addc_u32 s27, s21, 0
	s_waitcnt lgkmcnt(0)
	s_barrier
	v_cvt_pk_bf16_f32 v178, v178, v179
	v_cvt_pk_bf16_f32 v179, v180, v181
	v_cvt_pk_bf16_f32 v180, v182, v183
	v_cvt_pk_bf16_f32 v181, v184, v185
	v_cvt_pk_bf16_f32 v186, v186, v187
	v_cvt_pk_bf16_f32 v187, v188, v189
	v_cvt_pk_bf16_f32 v188, v190, v191
	v_cvt_pk_bf16_f32 v189, v192, v193
	global_store_dwordx4 v232, v[178:181], s[20:21]
	global_store_dwordx4 v232, v[186:189], s[26:27]
	v_readlane_b32 s20, v237, 20
	v_readlane_b32 s21, v237, 21
	v_readlane_b32 s32, v237, 22
	v_readlane_b32 s35, v237, 23
	ds_write_b32 v226, v194 offset:0
	ds_write_b32 v226, v195 offset:4
	ds_write_b32 v226, v196 offset:8
	ds_write_b32 v226, v197 offset:12
	ds_write_b32 v226, v198 offset:4160
	ds_write_b32 v226, v199 offset:4164
	ds_write_b32 v226, v200 offset:4168
	ds_write_b32 v226, v201 offset:4172
	ds_write_b32 v226, v202 offset:8320
	ds_write_b32 v226, v203 offset:8324
	ds_write_b32 v226, v204 offset:8328
	ds_write_b32 v226, v205 offset:8332
	ds_write_b32 v226, v206 offset:12480
	ds_write_b32 v226, v207 offset:12484
	ds_write_b32 v226, v208 offset:12488
	ds_write_b32 v226, v209 offset:12492
	v_mad_u32_u24 v232, v235, s35, v236
	s_waitcnt lgkmcnt(0)
	s_barrier
	ds_read2_b32 v[194:195], v227 offset1:65
	ds_read2_b32 v[196:197], v227 offset0:130 offset1:195
	ds_read2_b32 v[198:199], v228 offset0:4 offset1:69
	ds_read2_b32 v[200:201], v228 offset0:134 offset1:199
	ds_read2_b32 v[202:203], v229 offset1:65
	ds_read2_b32 v[204:205], v229 offset0:130 offset1:195
	ds_read2_b32 v[206:207], v230 offset0:4 offset1:69
	ds_read2_b32 v[208:209], v230 offset0:134 offset1:199
	s_add_u32 s26, s20, s32
	s_addc_u32 s27, s21, 0
	s_waitcnt lgkmcnt(0)
	s_barrier
	v_cvt_pk_bf16_f32 v194, v194, v195
	v_cvt_pk_bf16_f32 v195, v196, v197
	v_cvt_pk_bf16_f32 v196, v198, v199
	v_cvt_pk_bf16_f32 v197, v200, v201
	v_cvt_pk_bf16_f32 v202, v202, v203
	v_cvt_pk_bf16_f32 v203, v204, v205
	v_cvt_pk_bf16_f32 v204, v206, v207
	v_cvt_pk_bf16_f32 v205, v208, v209
	global_store_dwordx4 v232, v[194:197], s[20:21]
	global_store_dwordx4 v232, v[202:205], s[26:27]
	s_branch .Lwcm0_done
.Lwcm0_tail1:
	s_waitcnt vmcnt(0)
	v_readlane_b32 s20, v237, 16
	v_readlane_b32 s21, v237, 17
	v_readlane_b32 s32, v237, 18
	v_readlane_b32 s35, v237, 19
	ds_write_b32 v226, v178 offset:0
	ds_write_b32 v226, v179 offset:4
	ds_write_b32 v226, v180 offset:8
	ds_write_b32 v226, v181 offset:12
	ds_write_b32 v226, v182 offset:4160
	ds_write_b32 v226, v183 offset:4164
	ds_write_b32 v226, v184 offset:4168
	ds_write_b32 v226, v185 offset:4172
	ds_write_b32 v226, v186 offset:8320
	ds_write_b32 v226, v187 offset:8324
	ds_write_b32 v226, v188 offset:8328
	ds_write_b32 v226, v189 offset:8332
	ds_write_b32 v226, v190 offset:12480
	ds_write_b32 v226, v191 offset:12484
	ds_write_b32 v226, v192 offset:12488
	ds_write_b32 v226, v193 offset:12492
	v_mad_u32_u24 v232, v235, s35, v236
	s_waitcnt lgkmcnt(0)
	s_barrier
	ds_read2_b32 v[178:179], v227 offset1:65
	ds_read2_b32 v[180:181], v227 offset0:130 offset1:195
	ds_read2_b32 v[182:183], v228 offset0:4 offset1:69
	ds_read2_b32 v[184:185], v228 offset0:134 offset1:199
	ds_read2_b32 v[186:187], v229 offset1:65
	ds_read2_b32 v[188:189], v229 offset0:130 offset1:195
	ds_read2_b32 v[190:191], v230 offset0:4 offset1:69
	ds_read2_b32 v[192:193], v230 offset0:134 offset1:199
	s_add_u32 s26, s20, s32
	s_addc_u32 s27, s21, 0
	s_waitcnt lgkmcnt(0)
	s_barrier
	v_cvt_pk_bf16_f32 v178, v178, v179
	v_cvt_pk_bf16_f32 v179, v180, v181
	v_cvt_pk_bf16_f32 v180, v182, v183
	v_cvt_pk_bf16_f32 v181, v184, v185
	v_cvt_pk_bf16_f32 v186, v186, v187
	v_cvt_pk_bf16_f32 v187, v188, v189
	v_cvt_pk_bf16_f32 v188, v190, v191
	v_cvt_pk_bf16_f32 v189, v192, v193
	global_store_dwordx4 v232, v[178:181], s[20:21]
	global_store_dwordx4 v232, v[186:189], s[26:27]
	v_readlane_b32 s20, v237, 20
	v_readlane_b32 s21, v237, 21
	v_readlane_b32 s32, v237, 22
	v_readlane_b32 s35, v237, 23
	ds_write_b32 v226, v194 offset:0
	ds_write_b32 v226, v195 offset:4
	ds_write_b32 v226, v196 offset:8
	ds_write_b32 v226, v197 offset:12
	ds_write_b32 v226, v198 offset:4160
	ds_write_b32 v226, v199 offset:4164
	ds_write_b32 v226, v200 offset:4168
	ds_write_b32 v226, v201 offset:4172
	ds_write_b32 v226, v202 offset:8320
	ds_write_b32 v226, v203 offset:8324
	ds_write_b32 v226, v204 offset:8328
	ds_write_b32 v226, v205 offset:8332
	ds_write_b32 v226, v206 offset:12480
	ds_write_b32 v226, v207 offset:12484
	ds_write_b32 v226, v208 offset:12488
	ds_write_b32 v226, v209 offset:12492
	v_mad_u32_u24 v232, v235, s35, v236
	s_waitcnt lgkmcnt(0)
	s_barrier
	ds_read2_b32 v[194:195], v227 offset1:65
	ds_read2_b32 v[196:197], v227 offset0:130 offset1:195
	ds_read2_b32 v[198:199], v228 offset0:4 offset1:69
	ds_read2_b32 v[200:201], v228 offset0:134 offset1:199
	ds_read2_b32 v[202:203], v229 offset1:65
	ds_read2_b32 v[204:205], v229 offset0:130 offset1:195
	ds_read2_b32 v[206:207], v230 offset0:4 offset1:69
	ds_read2_b32 v[208:209], v230 offset0:134 offset1:199
	s_add_u32 s26, s20, s32
	s_addc_u32 s27, s21, 0
	s_waitcnt lgkmcnt(0)
	s_barrier
	v_cvt_pk_bf16_f32 v194, v194, v195
	v_cvt_pk_bf16_f32 v195, v196, v197
	v_cvt_pk_bf16_f32 v196, v198, v199
	v_cvt_pk_bf16_f32 v197, v200, v201
	v_cvt_pk_bf16_f32 v202, v202, v203
	v_cvt_pk_bf16_f32 v203, v204, v205
	v_cvt_pk_bf16_f32 v204, v206, v207
	v_cvt_pk_bf16_f32 v205, v208, v209
	global_store_dwordx4 v232, v[194:197], s[20:21]
	global_store_dwordx4 v232, v[202:205], s[26:27]
	v_readlane_b32 s20, v237, 8
	v_readlane_b32 s21, v237, 9
	v_readlane_b32 s32, v237, 10
	v_readlane_b32 s35, v237, 11
	ds_write_b32 v226, v146 offset:0
	ds_write_b32 v226, v147 offset:4
	ds_write_b32 v226, v148 offset:8
	ds_write_b32 v226, v149 offset:12
	ds_write_b32 v226, v150 offset:4160
	ds_write_b32 v226, v151 offset:4164
	ds_write_b32 v226, v152 offset:4168
	ds_write_b32 v226, v153 offset:4172
	ds_write_b32 v226, v154 offset:8320
	ds_write_b32 v226, v155 offset:8324
	ds_write_b32 v226, v156 offset:8328
	ds_write_b32 v226, v157 offset:8332
	ds_write_b32 v226, v158 offset:12480
	ds_write_b32 v226, v159 offset:12484
	ds_write_b32 v226, v160 offset:12488
	ds_write_b32 v226, v161 offset:12492
	v_mad_u32_u24 v232, v235, s35, v236
	s_waitcnt lgkmcnt(0)
	s_barrier
	ds_read2_b32 v[146:147], v227 offset1:65
	ds_read2_b32 v[148:149], v227 offset0:130 offset1:195
	ds_read2_b32 v[150:151], v228 offset0:4 offset1:69
	ds_read2_b32 v[152:153], v228 offset0:134 offset1:199
	ds_read2_b32 v[154:155], v229 offset1:65
	ds_read2_b32 v[156:157], v229 offset0:130 offset1:195
	ds_read2_b32 v[158:159], v230 offset0:4 offset1:69
	ds_read2_b32 v[160:161], v230 offset0:134 offset1:199
	s_add_u32 s26, s20, s32
	s_addc_u32 s27, s21, 0
	s_waitcnt lgkmcnt(0)
	s_barrier
	v_cvt_pk_bf16_f32 v146, v146, v147
	v_cvt_pk_bf16_f32 v147, v148, v149
	v_cvt_pk_bf16_f32 v148, v150, v151
	v_cvt_pk_bf16_f32 v149, v152, v153
	v_cvt_pk_bf16_f32 v154, v154, v155
	v_cvt_pk_bf16_f32 v155, v156, v157
	v_cvt_pk_bf16_f32 v156, v158, v159
	v_cvt_pk_bf16_f32 v157, v160, v161
	global_store_dwordx4 v232, v[146:149], s[20:21]
	global_store_dwordx4 v232, v[154:157], s[26:27]
	s_branch .Lwcm0_done
.Lwcm0_tail2:
	s_waitcnt vmcnt(0)
	v_readlane_b32 s20, v237, 20
	v_readlane_b32 s21, v237, 21
	v_readlane_b32 s32, v237, 22
	v_readlane_b32 s35, v237, 23
	ds_write_b32 v226, v194 offset:0
	ds_write_b32 v226, v195 offset:4
	ds_write_b32 v226, v196 offset:8
	ds_write_b32 v226, v197 offset:12
	ds_write_b32 v226, v198 offset:4160
	ds_write_b32 v226, v199 offset:4164
	ds_write_b32 v226, v200 offset:4168
	ds_write_b32 v226, v201 offset:4172
	ds_write_b32 v226, v202 offset:8320
	ds_write_b32 v226, v203 offset:8324
	ds_write_b32 v226, v204 offset:8328
	ds_write_b32 v226, v205 offset:8332
	ds_write_b32 v226, v206 offset:12480
	ds_write_b32 v226, v207 offset:12484
	ds_write_b32 v226, v208 offset:12488
	ds_write_b32 v226, v209 offset:12492
	v_mad_u32_u24 v232, v235, s35, v236
	s_waitcnt lgkmcnt(0)
	s_barrier
	ds_read2_b32 v[194:195], v227 offset1:65
	ds_read2_b32 v[196:197], v227 offset0:130 offset1:195
	ds_read2_b32 v[198:199], v228 offset0:4 offset1:69
	ds_read2_b32 v[200:201], v228 offset0:134 offset1:199
	ds_read2_b32 v[202:203], v229 offset1:65
	ds_read2_b32 v[204:205], v229 offset0:130 offset1:195
	ds_read2_b32 v[206:207], v230 offset0:4 offset1:69
	ds_read2_b32 v[208:209], v230 offset0:134 offset1:199
	s_add_u32 s26, s20, s32
	s_addc_u32 s27, s21, 0
	s_waitcnt lgkmcnt(0)
	s_barrier
	v_cvt_pk_bf16_f32 v194, v194, v195
	v_cvt_pk_bf16_f32 v195, v196, v197
	v_cvt_pk_bf16_f32 v196, v198, v199
	v_cvt_pk_bf16_f32 v197, v200, v201
	v_cvt_pk_bf16_f32 v202, v202, v203
	v_cvt_pk_bf16_f32 v203, v204, v205
	v_cvt_pk_bf16_f32 v204, v206, v207
	v_cvt_pk_bf16_f32 v205, v208, v209
	global_store_dwordx4 v232, v[194:197], s[20:21]
	global_store_dwordx4 v232, v[202:205], s[26:27]
	v_readlane_b32 s20, v237, 8
	v_readlane_b32 s21, v237, 9
	v_readlane_b32 s32, v237, 10
	v_readlane_b32 s35, v237, 11
	ds_write_b32 v226, v146 offset:0
	ds_write_b32 v226, v147 offset:4
	ds_write_b32 v226, v148 offset:8
	ds_write_b32 v226, v149 offset:12
	ds_write_b32 v226, v150 offset:4160
	ds_write_b32 v226, v151 offset:4164
	ds_write_b32 v226, v152 offset:4168
	ds_write_b32 v226, v153 offset:4172
	ds_write_b32 v226, v154 offset:8320
	ds_write_b32 v226, v155 offset:8324
	ds_write_b32 v226, v156 offset:8328
	ds_write_b32 v226, v157 offset:8332
	ds_write_b32 v226, v158 offset:12480
	ds_write_b32 v226, v159 offset:12484
	ds_write_b32 v226, v160 offset:12488
	ds_write_b32 v226, v161 offset:12492
	v_mad_u32_u24 v232, v235, s35, v236
	s_waitcnt lgkmcnt(0)
	s_barrier
	ds_read2_b32 v[146:147], v227 offset1:65
	ds_read2_b32 v[148:149], v227 offset0:130 offset1:195
	ds_read2_b32 v[150:151], v228 offset0:4 offset1:69
	ds_read2_b32 v[152:153], v228 offset0:134 offset1:199
	ds_read2_b32 v[154:155], v229 offset1:65
	ds_read2_b32 v[156:157], v229 offset0:130 offset1:195
	ds_read2_b32 v[158:159], v230 offset0:4 offset1:69
	ds_read2_b32 v[160:161], v230 offset0:134 offset1:199
	s_add_u32 s26, s20, s32
	s_addc_u32 s27, s21, 0
	s_waitcnt lgkmcnt(0)
	s_barrier
	v_cvt_pk_bf16_f32 v146, v146, v147
	v_cvt_pk_bf16_f32 v147, v148, v149
	v_cvt_pk_bf16_f32 v148, v150, v151
	v_cvt_pk_bf16_f32 v149, v152, v153
	v_cvt_pk_bf16_f32 v154, v154, v155
	v_cvt_pk_bf16_f32 v155, v156, v157
	v_cvt_pk_bf16_f32 v156, v158, v159
	v_cvt_pk_bf16_f32 v157, v160, v161
	global_store_dwordx4 v232, v[146:149], s[20:21]
	global_store_dwordx4 v232, v[154:157], s[26:27]
	v_readlane_b32 s20, v237, 12
	v_readlane_b32 s21, v237, 13
	v_readlane_b32 s32, v237, 14
	v_readlane_b32 s35, v237, 15
	ds_write_b32 v226, v162 offset:0
	ds_write_b32 v226, v163 offset:4
	ds_write_b32 v226, v164 offset:8
	ds_write_b32 v226, v165 offset:12
	ds_write_b32 v226, v166 offset:4160
	ds_write_b32 v226, v167 offset:4164
	ds_write_b32 v226, v168 offset:4168
	ds_write_b32 v226, v169 offset:4172
	ds_write_b32 v226, v170 offset:8320
	ds_write_b32 v226, v171 offset:8324
	ds_write_b32 v226, v172 offset:8328
	ds_write_b32 v226, v173 offset:8332
	ds_write_b32 v226, v174 offset:12480
	ds_write_b32 v226, v175 offset:12484
	ds_write_b32 v226, v176 offset:12488
	ds_write_b32 v226, v177 offset:12492
	v_mad_u32_u24 v232, v235, s35, v236
	s_waitcnt lgkmcnt(0)
	s_barrier
	ds_read2_b32 v[162:163], v227 offset1:65
	ds_read2_b32 v[164:165], v227 offset0:130 offset1:195
	ds_read2_b32 v[166:167], v228 offset0:4 offset1:69
	ds_read2_b32 v[168:169], v228 offset0:134 offset1:199
	ds_read2_b32 v[170:171], v229 offset1:65
	ds_read2_b32 v[172:173], v229 offset0:130 offset1:195
	ds_read2_b32 v[174:175], v230 offset0:4 offset1:69
	ds_read2_b32 v[176:177], v230 offset0:134 offset1:199
	s_add_u32 s26, s20, s32
	s_addc_u32 s27, s21, 0
	s_waitcnt lgkmcnt(0)
	s_barrier
	v_cvt_pk_bf16_f32 v162, v162, v163
	v_cvt_pk_bf16_f32 v163, v164, v165
	v_cvt_pk_bf16_f32 v164, v166, v167
	v_cvt_pk_bf16_f32 v165, v168, v169
	v_cvt_pk_bf16_f32 v170, v170, v171
	v_cvt_pk_bf16_f32 v171, v172, v173
	v_cvt_pk_bf16_f32 v172, v174, v175
	v_cvt_pk_bf16_f32 v173, v176, v177
	global_store_dwordx4 v232, v[162:165], s[20:21]
	global_store_dwordx4 v232, v[170:173], s[26:27]
	s_branch .Lwcm0_done

.Lwcm1_tj_3:
	s_load_dwordx2 s[8:9], s[0:1], s14
	s_add_u32 s20, s12, s36
	s_addc_u32 s21, s13, 0
	v_mad_u32_u24 v231, v233, s99, v234
	v_writelane_b32 v237, s20, 16
	v_writelane_b32 v237, s21, 17
	v_writelane_b32 v237, s32, 18
	v_writelane_b32 v237, s44, 19
	s_add_u32 s100, s100, s23
	s_waitcnt lgkmcnt(0)
	s_add_u32 s38, s8, s38
	s_addc_u32 s39, s9, 0
	global_load_dwordx4 v[178:181], v231, s[38:39] nt
	s_add_u32 s38, s38, s37
	s_addc_u32 s39, s39, 0
	global_load_dwordx4 v[182:185], v231, s[38:39] nt
	s_add_u32 s38, s38, s37
	s_addc_u32 s39, s39, 0
	global_load_dwordx4 v[186:189], v231, s[38:39] nt
	s_add_u32 s38, s38, s37
	s_addc_u32 s39, s39, 0
	global_load_dwordx4 v[190:193], v231, s[38:39] nt
	s_cmp_ge_u32 s100, s22
	s_cbranch_scc1 .Lwcm1_p3
	s_cmpk_ge_u32 s100, 0x900
	s_cbranch_scc1 .Lwcm1_t3_4
	s_cmpk_ge_u32 s100, 0x380
	s_cbranch_scc1 .Lwcm1_t2_4
	s_cmpk_ge_u32 s100, 0x280
	s_cbranch_scc1 .Lwcm1_t1_4
	s_movk_i32 s14, 0x78
	s_sub_u32 s99, s100, 0
	s_mul_i32 s44, s99, 0x66667
	s_lshr_b32 s44, s44, 24
	s_mul_i32 s36, s44, 40
	s_sub_u32 s99, s99, s36
	s_mul_i32 s38, s44, 0xa0000
	s_lshl_b32 s36, s99, 8
	s_add_u32 s38, s38, s36
	s_add_u32 s38, s38, 0xa00000
	s_lshl_b32 s36, s99, 6
	s_mov_b32 s32, 0x10000
	s_mul_i32 s36, s36, 0x800
	s_lshl_b32 s44, s44, 7
	s_add_u32 s36, s36, s44
	s_add_u32 s36, s36, 0x500000
	s_mov_b32 s37, 0x28000
	s_movk_i32 s44, 0x800
	s_mov_b32 s99, 0x2800
	s_branch .Lwcm1_tj_4

.Lwcm1_loop:
	s_waitcnt vmcnt(12)
	v_readlane_b32 s20, v237, 8
	v_readlane_b32 s21, v237, 9
	v_readlane_b32 s32, v237, 10
	v_readlane_b32 s35, v237, 11
	ds_write_b32 v226, v146 offset:0
	ds_write_b32 v226, v147 offset:4
	ds_write_b32 v226, v148 offset:8
	ds_write_b32 v226, v149 offset:12
	ds_write_b32 v226, v150 offset:4160
	ds_write_b32 v226, v151 offset:4164
	ds_write_b32 v226, v152 offset:4168
	ds_write_b32 v226, v153 offset:4172
	ds_write_b32 v226, v154 offset:8320
	ds_write_b32 v226, v155 offset:8324
	ds_write_b32 v226, v156 offset:8328
	ds_write_b32 v226, v157 offset:8332
	ds_write_b32 v226, v158 offset:12480
	ds_write_b32 v226, v159 offset:12484
	ds_write_b32 v226, v160 offset:12488
	ds_write_b32 v226, v161 offset:12492
	v_mad_u32_u24 v232, v235, s35, v236
	s_waitcnt lgkmcnt(0)
	s_barrier
	ds_read2_b32 v[146:147], v227 offset1:65
	ds_read2_b32 v[148:149], v227 offset0:130 offset1:195
	ds_read2_b32 v[150:151], v228 offset0:4 offset1:69
	ds_read2_b32 v[152:153], v228 offset0:134 offset1:199
	ds_read2_b32 v[154:155], v229 offset1:65
	ds_read2_b32 v[156:157], v229 offset0:130 offset1:195
	ds_read2_b32 v[158:159], v230 offset0:4 offset1:69
	ds_read2_b32 v[160:161], v230 offset0:134 offset1:199
	s_add_u32 s26, s20, s32
	s_addc_u32 s27, s21, 0
	s_waitcnt lgkmcnt(0)
	s_barrier
	v_cvt_pk_bf16_f32 v146, v146, v147
	v_cvt_pk_bf16_f32 v147, v148, v149
	v_cvt_pk_bf16_f32 v148, v150, v151
	v_cvt_pk_bf16_f32 v149, v152, v153
	v_cvt_pk_bf16_f32 v154, v154, v155
	v_cvt_pk_bf16_f32 v155, v156, v157
	v_cvt_pk_bf16_f32 v156, v158, v159
	v_cvt_pk_bf16_f32 v157, v160, v161
	global_store_dwordx4 v232, v[146:149], s[20:21]
	global_store_dwordx4 v232, v[154:157], s[26:27]
	s_cmp_ge_u32 s100, s22
	s_cbranch_scc1 .Lwcm1_tail0
	s_cmpk_ge_u32 s100, 0x900
	s_cbranch_scc1 .Lwcm1_t3_5
	s_cmpk_ge_u32 s100, 0x380
	s_cbranch_scc1 .Lwcm1_t2_5
	s_cmpk_ge_u32 s100, 0x280
	s_cbranch_scc1 .Lwcm1_t1_5
	s_movk_i32 s14, 0x78
	s_sub_u32 s99, s100, 0
	s_mul_i32 s44, s99, 0x66667
	s_lshr_b32 s44, s44, 24
	s_mul_i32 s36, s44, 40
	s_sub_u32 s99, s99, s36
	s_mul_i32 s38, s44, 0xa0000
	s_lshl_b32 s36, s99, 8
	s_add_u32 s38, s38, s36
	s_add_u32 s38, s38, 0xa00000
	s_lshl_b32 s36, s99, 6
	s_mov_b32 s32, 0x10000
	s_mul_i32 s36, s36, 0x800
	s_lshl_b32 s44, s44, 7
	s_add_u32 s36, s36, s44
	s_add_u32 s36, s36, 0x500000
	s_mov_b32 s37, 0x28000
	s_movk_i32 s44, 0x800
	s_mov_b32 s99, 0x2800
	s_branch .Lwcm1_tj_5

.Lwcm1_tj_5:
	s_load_dwordx2 s[8:9], s[0:1], s14
	s_add_u32 s20, s12, s36
	s_addc_u32 s21, s13, 0
	v_mad_u32_u24 v231, v233, s99, v234
	v_writelane_b32 v237, s20, 8
	v_writelane_b32 v237, s21, 9
	v_writelane_b32 v237, s32, 10
	v_writelane_b32 v237, s44, 11
	s_add_u32 s100, s100, s23
	s_waitcnt lgkmcnt(0)
	s_add_u32 s38, s8, s38
	s_addc_u32 s39, s9, 0
	global_load_dwordx4 v[146:149], v231, s[38:39] nt
	s_add_u32 s38, s38, s37
	s_addc_u32 s39, s39, 0
	global_load_dwordx4 v[150:153], v231, s[38:39] nt
	s_add_u32 s38, s38, s37
	s_addc_u32 s39, s39, 0
	global_load_dwordx4 v[154:157], v231, s[38:39] nt
	s_add_u32 s38, s38, s37
	s_addc_u32 s39, s39, 0
	global_load_dwordx4 v[158:161], v231, s[38:39] nt
	s_waitcnt vmcnt(12)
	v_readlane_b32 s20, v237, 12
	v_readlane_b32 s21, v237, 13
	v_readlane_b32 s32, v237, 14
	v_readlane_b32 s35, v237, 15
	ds_write_b32 v226, v162 offset:0
	ds_write_b32 v226, v163 offset:4
	ds_write_b32 v226, v164 offset:8
	ds_write_b32 v226, v165 offset:12
	ds_write_b32 v226, v166 offset:4160
	ds_write_b32 v226, v167 offset:4164
	ds_write_b32 v226, v168 offset:4168
	ds_write_b32 v226, v169 offset:4172
	ds_write_b32 v226, v170 offset:8320
	ds_write_b32 v226, v171 offset:8324
	ds_write_b32 v226, v172 offset:8328
	ds_write_b32 v226, v173 offset:8332
	ds_write_b32 v226, v174 offset:12480
	ds_write_b32 v226, v175 offset:12484
	ds_write_b32 v226, v176 offset:12488
	ds_write_b32 v226, v177 offset:12492
	v_mad_u32_u24 v232, v235, s35, v236
	s_waitcnt lgkmcnt(0)
	s_barrier
	ds_read2_b32 v[162:163], v227 offset1:65
	ds_read2_b32 v[164:165], v227 offset0:130 offset1:195
	ds_read2_b32 v[166:167], v228 offset0:4 offset1:69
	ds_read2_b32 v[168:169], v228 offset0:134 offset1:199
	ds_read2_b32 v[170:171], v229 offset1:65
	ds_read2_b32 v[172:173], v229 offset0:130 offset1:195
	ds_read2_b32 v[174:175], v230 offset0:4 offset1:69
	ds_read2_b32 v[176:177], v230 offset0:134 offset1:199
	s_add_u32 s26, s20, s32
	s_addc_u32 s27, s21, 0
	s_waitcnt lgkmcnt(0)
	s_barrier
	v_cvt_pk_bf16_f32 v162, v162, v163
	v_cvt_pk_bf16_f32 v163, v164, v165
	v_cvt_pk_bf16_f32 v164, v166, v167
	v_cvt_pk_bf16_f32 v165, v168, v169
	v_cvt_pk_bf16_f32 v170, v170, v171
	v_cvt_pk_bf16_f32 v171, v172, v173
	v_cvt_pk_bf16_f32 v172, v174, v175
	v_cvt_pk_bf16_f32 v173, v176, v177
	global_store_dwordx4 v232, v[162:165], s[20:21]
	global_store_dwordx4 v232, v[170:173], s[26:27]
	s_cmp_ge_u32 s100, s22
	s_cbranch_scc1 .Lwcm1_tail1
	s_cmpk_ge_u32 s100, 0x900
	s_cbranch_scc1 .Lwcm1_t3_6
	s_cmpk_ge_u32 s100, 0x380
	s_cbranch_scc1 .Lwcm1_t2_6
	s_cmpk_ge_u32 s100, 0x280
	s_cbranch_scc1 .Lwcm1_t1_6
	s_movk_i32 s14, 0x78
	s_sub_u32 s99, s100, 0
	s_mul_i32 s44, s99, 0x66667
	s_lshr_b32 s44, s44, 24
	s_mul_i32 s36, s44, 40
	s_sub_u32 s99, s99, s36
	s_mul_i32 s38, s44, 0xa0000
	s_lshl_b32 s36, s99, 8
	s_add_u32 s38, s38, s36
	s_add_u32 s38, s38, 0xa00000
	s_lshl_b32 s36, s99, 6
	s_mov_b32 s32, 0x10000
	s_mul_i32 s36, s36, 0x800
	s_lshl_b32 s44, s44, 7
	s_add_u32 s36, s36, s44
	s_add_u32 s36, s36, 0x500000
	s_mov_b32 s37, 0x28000
	s_movk_i32 s44, 0x800
	s_mov_b32 s99, 0x2800
	s_branch .Lwcm1_tj_6

.Lwcm1_tj_6:
	s_load_dwordx2 s[8:9], s[0:1], s14
	s_add_u32 s20, s12, s36
	s_addc_u32 s21, s13, 0
	v_mad_u32_u24 v231, v233, s99, v234
	v_writelane_b32 v237, s20, 12
	v_writelane_b32 v237, s21, 13
	v_writelane_b32 v237, s32, 14
	v_writelane_b32 v237, s44, 15
	s_add_u32 s100, s100, s23
	s_waitcnt lgkmcnt(0)
	s_add_u32 s38, s8, s38
	s_addc_u32 s39, s9, 0
	global_load_dwordx4 v[162:165], v231, s[38:39] nt
	s_add_u32 s38, s38, s37
	s_addc_u32 s39, s39, 0
	global_load_dwordx4 v[166:169], v231, s[38:39] nt
	s_add_u32 s38, s38, s37
	s_addc_u32 s39, s39, 0
	global_load_dwordx4 v[170:173], v231, s[38:39] nt
	s_add_u32 s38, s38, s37
	s_addc_u32 s39, s39, 0
	global_load_dwordx4 v[174:177], v231, s[38:39] nt
	s_waitcnt vmcnt(12)
	v_readlane_b32 s20, v237, 16
	v_readlane_b32 s21, v237, 17
	v_readlane_b32 s32, v237, 18
	v_readlane_b32 s35, v237, 19
	ds_write_b32 v226, v178 offset:0
	ds_write_b32 v226, v179 offset:4
	ds_write_b32 v226, v180 offset:8
	ds_write_b32 v226, v181 offset:12
	ds_write_b32 v226, v182 offset:4160
	ds_write_b32 v226, v183 offset:4164
	ds_write_b32 v226, v184 offset:4168
	ds_write_b32 v226, v185 offset:4172
	ds_write_b32 v226, v186 offset:8320
	ds_write_b32 v226, v187 offset:8324
	ds_write_b32 v226, v188 offset:8328
	ds_write_b32 v226, v189 offset:8332
	ds_write_b32 v226, v190 offset:12480
	ds_write_b32 v226, v191 offset:12484
	ds_write_b32 v226, v192 offset:12488
	ds_write_b32 v226, v193 offset:12492
	v_mad_u32_u24 v232, v235, s35, v236
	s_waitcnt lgkmcnt(0)
	s_barrier
	ds_read2_b32 v[178:179], v227 offset1:65
	ds_read2_b32 v[180:181], v227 offset0:130 offset1:195
	ds_read2_b32 v[182:183], v228 offset0:4 offset1:69
	ds_read2_b32 v[184:185], v228 offset0:134 offset1:199
	ds_read2_b32 v[186:187], v229 offset1:65
	ds_read2_b32 v[188:189], v229 offset0:130 offset1:195
	ds_read2_b32 v[190:191], v230 offset0:4 offset1:69
	ds_read2_b32 v[192:193], v230 offset0:134 offset1:199
	s_add_u32 s26, s20, s32
	s_addc_u32 s27, s21, 0
	s_waitcnt lgkmcnt(0)
	s_barrier
	v_cvt_pk_bf16_f32 v178, v178, v179
	v_cvt_pk_bf16_f32 v179, v180, v181
	v_cvt_pk_bf16_f32 v180, v182, v183
	v_cvt_pk_bf16_f32 v181, v184, v185
	v_cvt_pk_bf16_f32 v186, v186, v187
	v_cvt_pk_bf16_f32 v187, v188, v189
	v_cvt_pk_bf16_f32 v188, v190, v191
	v_cvt_pk_bf16_f32 v189, v192, v193
	global_store_dwordx4 v232, v[178:181], s[20:21]
	global_store_dwordx4 v232, v[186:189], s[26:27]
	s_cmp_ge_u32 s100, s22
	s_cbranch_scc1 .Lwcm1_tail2
	s_cmpk_ge_u32 s100, 0x900
	s_cbranch_scc1 .Lwcm1_t3_7
	s_cmpk_ge_u32 s100, 0x380
	s_cbranch_scc1 .Lwcm1_t2_7
	s_cmpk_ge_u32 s100, 0x280
	s_cbranch_scc1 .Lwcm1_t1_7
	s_movk_i32 s14, 0x78
	s_sub_u32 s99, s100, 0
	s_mul_i32 s44, s99, 0x66667
	s_lshr_b32 s44, s44, 24
	s_mul_i32 s36, s44, 40
	s_sub_u32 s99, s99, s36
	s_mul_i32 s38, s44, 0xa0000
	s_lshl_b32 s36, s99, 8
	s_add_u32 s38, s38, s36
	s_add_u32 s38, s38, 0xa00000
	s_lshl_b32 s36, s99, 6
	s_mov_b32 s32, 0x10000
	s_mul_i32 s36, s36, 0x800
	s_lshl_b32 s44, s44, 7
	s_add_u32 s36, s36, s44
	s_add_u32 s36, s36, 0x500000
	s_mov_b32 s37, 0x28000
	s_movk_i32 s44, 0x800
	s_mov_b32 s99, 0x2800
	s_branch .Lwcm1_tj_7

.Lwcm1_tj_7:
	s_load_dwordx2 s[8:9], s[0:1], s14
	s_add_u32 s20, s12, s36
	s_addc_u32 s21, s13, 0
	v_mad_u32_u24 v231, v233, s99, v234
	v_writelane_b32 v237, s20, 16
	v_writelane_b32 v237, s21, 17
	v_writelane_b32 v237, s32, 18
	v_writelane_b32 v237, s44, 19
	s_add_u32 s100, s100, s23
	s_waitcnt lgkmcnt(0)
	s_add_u32 s38, s8, s38
	s_addc_u32 s39, s9, 0
	global_load_dwordx4 v[178:181], v231, s[38:39] nt
	s_add_u32 s38, s38, s37
	s_addc_u32 s39, s39, 0
	global_load_dwordx4 v[182:185], v231, s[38:39] nt
	s_add_u32 s38, s38, s37
	s_addc_u32 s39, s39, 0
	global_load_dwordx4 v[186:189], v231, s[38:39] nt
	s_add_u32 s38, s38, s37
	s_addc_u32 s39, s39, 0
	global_load_dwordx4 v[190:193], v231, s[38:39] nt
	s_waitcnt vmcnt(12)
	v_readlane_b32 s20, v237, 20
	v_readlane_b32 s21, v237, 21
	v_readlane_b32 s32, v237, 22
	v_readlane_b32 s35, v237, 23
	ds_write_b32 v226, v194 offset:0
	ds_write_b32 v226, v195 offset:4
	ds_write_b32 v226, v196 offset:8
	ds_write_b32 v226, v197 offset:12
	ds_write_b32 v226, v198 offset:4160
	ds_write_b32 v226, v199 offset:4164
	ds_write_b32 v226, v200 offset:4168
	ds_write_b32 v226, v201 offset:4172
	ds_write_b32 v226, v202 offset:8320
	ds_write_b32 v226, v203 offset:8324
	ds_write_b32 v226, v204 offset:8328
	ds_write_b32 v226, v205 offset:8332
	ds_write_b32 v226, v206 offset:12480
	ds_write_b32 v226, v207 offset:12484
	ds_write_b32 v226, v208 offset:12488
	ds_write_b32 v226, v209 offset:12492
	v_mad_u32_u24 v232, v235, s35, v236
	s_waitcnt lgkmcnt(0)
	s_barrier
	ds_read2_b32 v[194:195], v227 offset1:65
	ds_read2_b32 v[196:197], v227 offset0:130 offset1:195
	ds_read2_b32 v[198:199], v228 offset0:4 offset1:69
	ds_read2_b32 v[200:201], v228 offset0:134 offset1:199
	ds_read2_b32 v[202:203], v229 offset1:65
	ds_read2_b32 v[204:205], v229 offset0:130 offset1:195
	ds_read2_b32 v[206:207], v230 offset0:4 offset1:69
	ds_read2_b32 v[208:209], v230 offset0:134 offset1:199
	s_add_u32 s26, s20, s32
	s_addc_u32 s27, s21, 0
	s_waitcnt lgkmcnt(0)
	s_barrier
	v_cvt_pk_bf16_f32 v194, v194, v195
	v_cvt_pk_bf16_f32 v195, v196, v197
	v_cvt_pk_bf16_f32 v196, v198, v199
	v_cvt_pk_bf16_f32 v197, v200, v201
	v_cvt_pk_bf16_f32 v202, v202, v203
	v_cvt_pk_bf16_f32 v203, v204, v205
	v_cvt_pk_bf16_f32 v204, v206, v207
	v_cvt_pk_bf16_f32 v205, v208, v209
	global_store_dwordx4 v232, v[194:197], s[20:21]
	global_store_dwordx4 v232, v[202:205], s[26:27]
	s_cmp_ge_u32 s100, s22
	s_cbranch_scc1 .Lwcm1_tail3
	s_cmpk_ge_u32 s100, 0x900
	s_cbranch_scc1 .Lwcm1_t3_8
	s_cmpk_ge_u32 s100, 0x380
	s_cbranch_scc1 .Lwcm1_t2_8
	s_cmpk_ge_u32 s100, 0x280
	s_cbranch_scc1 .Lwcm1_t1_8
	s_movk_i32 s14, 0x78
	s_sub_u32 s99, s100, 0
	s_mul_i32 s44, s99, 0x66667
	s_lshr_b32 s44, s44, 24
	s_mul_i32 s36, s44, 40
	s_sub_u32 s99, s99, s36
	s_mul_i32 s38, s44, 0xa0000
	s_lshl_b32 s36, s99, 8
	s_add_u32 s38, s38, s36
	s_add_u32 s38, s38, 0xa00000
	s_lshl_b32 s36, s99, 6
	s_mov_b32 s32, 0x10000
	s_mul_i32 s36, s36, 0x800
	s_lshl_b32 s44, s44, 7
	s_add_u32 s36, s36, s44
	s_add_u32 s36, s36, 0x500000
	s_mov_b32 s37, 0x28000
	s_movk_i32 s44, 0x800
	s_mov_b32 s99, 0x2800
	s_branch .Lwcm1_tj_8
